# trimmed redundant lgkmcnt wait after MMA-opening barrier and mid-segment setprio pair in all four GEMM loops (on top of saddr LDS-DMA + straight-line row scales)
# speedup vs baseline: 1.0014x; 1.0014x over previous
; #define PG8_STAGE(bufoff, gbase, voff) do { _Pragma("unroll") for (int _i = 0; _i < 2; ++_i) \
;         __builtin_amdgcn_global_load_lds((const unsigned*)((const char*)(gbase) + (voff)[_i]), (PG8_LAS unsigned*)(lds + (bufoff) + ldsw + _i * 8192), 16, 0, 0); } while (0)
; #define PG8_LDA(dst, b, h) do { _Pragma("unroll") for (int m = 0; m < 4; ++m) _Pragma("unroll") for (int k = 0; k < 2; ++k) dst[m][k] = *(const PG8_LAS bf16x8*)(lds + PG8_SA(b, h) + aoff + m * 2048 + k * 1024); } while (0)
; #define PG8_LDB(dst, b, h) do { _Pragma("unroll") for (int n = 0; n < 2; ++n) _Pragma("unroll") for (int k = 0; k < 2; ++k) dst[n][k] = *(const PG8_LAS bf16x8*)(lds + PG8_SB(b, h) + boff + n * 2048 + k * 1024); } while (0)
; #define PG8_MMA(ai, bj, At, Bt) do { __builtin_amdgcn_s_setprio(1); _Pragma("unroll") for (int m = 0; m < 4; ++m) _Pragma("unroll") for (int n = 0; n < 2; ++n) _Pragma("unroll") for (int k = 0; k < 2; ++k) \
;         acc[ai][bj][m][n] = __builtin_amdgcn_mfma_f32_16x16x32_bf16(Bt[n][k], At[m][k], acc[ai][bj][m][n], 0, 0, 0); __builtin_amdgcn_s_setprio(0); } while (0)
; #define PG8_WAIT_V(n) asm volatile("s_waitcnt vmcnt(" #n ")" ::: "memory")
; #define PG8_WAIT_L(n) asm volatile("s_waitcnt lgkmcnt(" #n ")" ::: "memory")
; template <class Epi, class Sched, bool ALIGN_EPI = false, bool SP2 = false>
; __device__ __forceinline__ void gemm_phase(PG8_LAS unsigned char* lds, const Gemm g, const Sched& S, const Epi& E) {
;     ...
;             const bool last = (t == nt - 2);
;             const char* a1 = cA + (size_t)(t + 1) * kstep;
;             const char* a2 = last ? nA : cA + (size_t)(t + 2) * kstep; const char* b2 = last ? nB : cB + (size_t)(t + 2) * kstep;
;             const char* a3 = a2 + kstep; const char* b3 = b2 + kstep;
;             if (last && has_next) S.a_ready(nxt);
;             if constexpr (SP2) {
;             PG8_LDB(B0, 0, 0); PG8_LDB(B1, 0, 1); PG8_SCHED; PG8_LDA(At, 0, 0); PG8_STAGE(PG8_SA(1, 1), a1 + hstep, voffA);
;             PG8_WAIT_V(8); PG8_WAIT_L(0); PG8_BAR; PG8_MMA(0, 0, At, B0); PG8_MMA(0, 1, At, B1); PG8_BAR; PG8_SCHED;
;             PG8_LDA(At, 0, 1); PG8_STAGE(PG8_SB(0, 0), b2, voffB); PG8_STAGE(PG8_SB(0, 1), b2 + hstep, voffB); PG8_STAGE(PG8_SA(0, 0), a2, voffA);
;             PG8_WAIT_V(8); PG8_WAIT_L(0); PG8_BAR; PG8_MMA(1, 0, At, B0); PG8_MMA(1, 1, At, B1); PG8_BAR; PG8_SCHED;
.LBB0_65:
	s_add_u32 s20, s18, 0xfffc0080
	s_addc_u32 s21, s19, -1
	s_cmp_eq_u32 s49, 12
	s_cselect_b32 s23, s11, s21
	s_cselect_b32 s22, s45, s20
	s_cselect_b32 s21, s9, s48
	s_cselect_b32 s20, s46, s47
	ds_read_b128 v[146:149], v216
	ds_read_b128 v[150:153], v216 offset:1024
	ds_read_b128 v[154:157], v216 offset:2048
	ds_read_b128 v[158:161], v216 offset:3072
	ds_read_b128 v[162:165], v216 offset:16384
	ds_read_b128 v[166:169], v216 offset:17408
	ds_read_b128 v[170:173], v216 offset:18432
	ds_read_b128 v[174:177], v216 offset:19456
	s_add_i32 m0, s34, 0xc000
	ds_read_b128 v[178:181], v144
	ds_read_b128 v[188:191], v144 offset:1024
	ds_read_b128 v[192:195], v144 offset:2048
	ds_read_b128 v[196:199], v144 offset:3072
	ds_read_b128 v[200:203], v144 offset:4096
	ds_read_b128 v[204:207], v144 offset:5120
	ds_read_b128 v[208:211], v144 offset:6144
	ds_read_b128 v[212:215], v144 offset:7168
	global_load_lds_dwordx4 v136, s[18:19]
	s_add_i32 m0, s34, 0xe000
	s_add_i32 s50, s33, 0x10000
	global_load_lds_dwordx4 v138, s[18:19]
	s_waitcnt vmcnt(8)
	s_waitcnt lgkmcnt(0)
	s_barrier
	s_setprio 1
	v_mfma_f32_16x16x32_bf16 v[126:129], v[146:149], v[178:181], v[126:129]
	v_mfma_f32_16x16x32_bf16 v[118:121], v[154:157], v[178:181], v[118:121]
	v_mfma_f32_16x16x32_bf16 v[110:113], v[146:149], v[192:195], v[110:113]
	v_mfma_f32_16x16x32_bf16 v[102:105], v[154:157], v[192:195], v[102:105]
	v_mfma_f32_16x16x32_bf16 v[94:97], v[146:149], v[200:203], v[94:97]
	v_mfma_f32_16x16x32_bf16 v[86:89], v[154:157], v[200:203], v[86:89]
	v_mfma_f32_16x16x32_bf16 v[78:81], v[146:149], v[208:211], v[78:81]
	v_mfma_f32_16x16x32_bf16 v[70:73], v[154:157], v[208:211], v[70:73]
	v_mfma_f32_16x16x32_bf16 v[126:129], v[150:153], v[188:191], v[126:129]
	v_mfma_f32_16x16x32_bf16 v[118:121], v[158:161], v[188:191], v[118:121]
	v_mfma_f32_16x16x32_bf16 v[110:113], v[150:153], v[196:199], v[110:113]
	v_mfma_f32_16x16x32_bf16 v[102:105], v[158:161], v[196:199], v[102:105]
	v_mfma_f32_16x16x32_bf16 v[94:97], v[150:153], v[204:207], v[94:97]
	v_mfma_f32_16x16x32_bf16 v[86:89], v[158:161], v[204:207], v[86:89]
	v_mfma_f32_16x16x32_bf16 v[78:81], v[150:153], v[212:215], v[78:81]
	v_mfma_f32_16x16x32_bf16 v[70:73], v[158:161], v[212:215], v[70:73]
	v_mfma_f32_16x16x32_bf16 v[122:125], v[162:165], v[178:181], v[122:125]
	v_mfma_f32_16x16x32_bf16 v[114:117], v[170:173], v[178:181], v[114:117]
	v_mfma_f32_16x16x32_bf16 v[106:109], v[162:165], v[192:195], v[106:109]
	v_mfma_f32_16x16x32_bf16 v[98:101], v[170:173], v[192:195], v[98:101]
	v_mfma_f32_16x16x32_bf16 v[90:93], v[162:165], v[200:203], v[90:93]
	v_mfma_f32_16x16x32_bf16 v[82:85], v[170:173], v[200:203], v[82:85]
	v_mfma_f32_16x16x32_bf16 v[74:77], v[162:165], v[208:211], v[74:77]
	v_mfma_f32_16x16x32_bf16 v[66:69], v[170:173], v[208:211], v[66:69]
	v_mfma_f32_16x16x32_bf16 v[122:125], v[166:169], v[188:191], v[122:125]
	v_mfma_f32_16x16x32_bf16 v[114:117], v[174:177], v[188:191], v[114:117]
	v_mfma_f32_16x16x32_bf16 v[106:109], v[166:169], v[196:199], v[106:109]
	v_mfma_f32_16x16x32_bf16 v[98:101], v[174:177], v[196:199], v[98:101]
	v_mfma_f32_16x16x32_bf16 v[90:93], v[166:169], v[204:207], v[90:93]
	v_mfma_f32_16x16x32_bf16 v[82:85], v[174:177], v[204:207], v[82:85]
	v_mfma_f32_16x16x32_bf16 v[74:77], v[166:169], v[212:215], v[74:77]
	v_mfma_f32_16x16x32_bf16 v[66:69], v[174:177], v[212:215], v[66:69]
	s_setprio 0
	s_barrier
	s_mov_b32 m0, s50
	ds_read_b128 v[178:181], v144 offset:16384
	ds_read_b128 v[188:191], v144 offset:17408
	ds_read_b128 v[192:195], v144 offset:18432
	ds_read_b128 v[196:199], v144 offset:19456
	ds_read_b128 v[200:203], v144 offset:20480
	ds_read_b128 v[204:207], v144 offset:21504
	ds_read_b128 v[208:211], v144 offset:22528
	ds_read_b128 v[212:215], v144 offset:23552
	global_load_lds_dwordx4 v64, s[20:21]
	s_add_i32 m0, s50, 0x2000
	s_add_u32 s98, s20, 0x40000
	s_addc_u32 s99, s21, 0
	global_load_lds_dwordx4 v130, s[20:21]
	s_add_i32 m0, s33, 0x14000
	s_nop 0
	global_load_lds_dwordx4 v64, s[98:99]
	s_add_i32 m0, s33, 0x16000
	s_nop 0
	global_load_lds_dwordx4 v130, s[98:99]
	s_mov_b32 m0, s34
	s_nop 0
	global_load_lds_dwordx4 v134, s[22:23]
	s_mov_b32 m0, s35
	s_nop 0
	global_load_lds_dwordx4 v132, s[22:23]
	s_waitcnt vmcnt(8)
	s_waitcnt lgkmcnt(0)
	s_barrier
	s_setprio 1
	v_mfma_f32_16x16x32_bf16 v[60:63], v[146:149], v[178:181], v[60:63]
	v_mfma_f32_16x16x32_bf16 v[52:55], v[154:157], v[178:181], v[52:55]
	v_mfma_f32_16x16x32_bf16 v[44:47], v[146:149], v[192:195], v[44:47]
	v_mfma_f32_16x16x32_bf16 v[36:39], v[154:157], v[192:195], v[36:39]
	v_mfma_f32_16x16x32_bf16 v[28:31], v[146:149], v[200:203], v[28:31]
	v_mfma_f32_16x16x32_bf16 v[20:23], v[154:157], v[200:203], v[20:23]
	v_mfma_f32_16x16x32_bf16 v[12:15], v[146:149], v[208:211], v[12:15]
	v_mfma_f32_16x16x32_bf16 v[4:7], v[154:157], v[208:211], v[4:7]
	v_mfma_f32_16x16x32_bf16 v[60:63], v[150:153], v[188:191], v[60:63]
	v_mfma_f32_16x16x32_bf16 v[52:55], v[158:161], v[188:191], v[52:55]
	v_mfma_f32_16x16x32_bf16 v[44:47], v[150:153], v[196:199], v[44:47]
	v_mfma_f32_16x16x32_bf16 v[36:39], v[158:161], v[196:199], v[36:39]
	v_mfma_f32_16x16x32_bf16 v[28:31], v[150:153], v[204:207], v[28:31]
	v_mfma_f32_16x16x32_bf16 v[20:23], v[158:161], v[204:207], v[20:23]
	v_mfma_f32_16x16x32_bf16 v[12:15], v[150:153], v[212:215], v[12:15]
	v_mfma_f32_16x16x32_bf16 v[4:7], v[158:161], v[212:215], v[4:7]
	v_mfma_f32_16x16x32_bf16 v[56:59], v[162:165], v[178:181], v[56:59]
	v_mfma_f32_16x16x32_bf16 v[48:51], v[170:173], v[178:181], v[48:51]
	v_mfma_f32_16x16x32_bf16 v[40:43], v[162:165], v[192:195], v[40:43]
	v_mfma_f32_16x16x32_bf16 v[32:35], v[170:173], v[192:195], v[32:35]
	v_mfma_f32_16x16x32_bf16 v[24:27], v[162:165], v[200:203], v[24:27]
	v_mfma_f32_16x16x32_bf16 v[16:19], v[170:173], v[200:203], v[16:19]
	v_mfma_f32_16x16x32_bf16 v[8:11], v[162:165], v[208:211], v[8:11]
	v_mfma_f32_16x16x32_bf16 v[0:3], v[170:173], v[208:211], v[0:3]
	v_mfma_f32_16x16x32_bf16 v[56:59], v[166:169], v[188:191], v[56:59]
	v_mfma_f32_16x16x32_bf16 v[48:51], v[174:177], v[188:191], v[48:51]
	v_mfma_f32_16x16x32_bf16 v[40:43], v[166:169], v[196:199], v[40:43]
	v_mfma_f32_16x16x32_bf16 v[32:35], v[174:177], v[196:199], v[32:35]
	v_mfma_f32_16x16x32_bf16 v[24:27], v[166:169], v[204:207], v[24:27]
	v_mfma_f32_16x16x32_bf16 v[16:19], v[174:177], v[204:207], v[16:19]
	v_mfma_f32_16x16x32_bf16 v[8:11], v[166:169], v[212:215], v[8:11]
	v_mfma_f32_16x16x32_bf16 v[0:3], v[174:177], v[212:215], v[0:3]
	s_setprio 0
	s_barrier
; #define PG8_STAGE(bufoff, gbase, voff) do { _Pragma("unroll") for (int _i = 0; _i < 2; ++_i) \
;         __builtin_amdgcn_global_load_lds((const unsigned*)((const char*)(gbase) + (voff)[_i]), (PG8_LAS unsigned*)(lds + (bufoff) + ldsw + _i * 8192), 16, 0, 0); } while (0)
; #define PG8_LDA(dst, b, h) do { _Pragma("unroll") for (int m = 0; m < 4; ++m) _Pragma("unroll") for (int k = 0; k < 2; ++k) dst[m][k] = *(const PG8_LAS bf16x8*)(lds + PG8_SA(b, h) + aoff + m * 2048 + k * 1024); } while (0)
; #define PG8_LDB(dst, b, h) do { _Pragma("unroll") for (int n = 0; n < 2; ++n) _Pragma("unroll") for (int k = 0; k < 2; ++k) dst[n][k] = *(const PG8_LAS bf16x8*)(lds + PG8_SB(b, h) + boff + n * 2048 + k * 1024); } while (0)
; #define PG8_MMA(ai, bj, At, Bt) do { __builtin_amdgcn_s_setprio(1); _Pragma("unroll") for (int m = 0; m < 4; ++m) _Pragma("unroll") for (int n = 0; n < 2; ++n) _Pragma("unroll") for (int k = 0; k < 2; ++k) \
;         acc[ai][bj][m][n] = __builtin_amdgcn_mfma_f32_16x16x32_bf16(Bt[n][k], At[m][k], acc[ai][bj][m][n], 0, 0, 0); __builtin_amdgcn_s_setprio(0); } while (0)
; #define PG8_WAIT_V(n) asm volatile("s_waitcnt vmcnt(" #n ")" ::: "memory")
; #define PG8_WAIT_L(n) asm volatile("s_waitcnt lgkmcnt(" #n ")" ::: "memory")
; #define PG8_BAR __builtin_amdgcn_s_barrier()
; #define PG8_SCHED __builtin_amdgcn_sched_barrier(0)
; template <class Epi, class Sched, bool ALIGN_EPI = false, bool SP2 = false>
; __device__ __forceinline__ void gemm_phase(PG8_LAS unsigned char* lds, const Gemm g, const Sched& S, const Epi& E) {
;     ...
;             PG8_LDB(B0, 1, 0); PG8_LDB(B1, 1, 1); PG8_SCHED; PG8_LDA(At, 1, 0); PG8_STAGE(PG8_SA(0, 1), a2 + hstep, voffA);
;             PG8_WAIT_V(8); PG8_WAIT_L(0); PG8_BAR; PG8_MMA(0, 0, At, B0); PG8_MMA(0, 1, At, B1); PG8_BAR; PG8_SCHED;
;             PG8_LDA(At, 1, 1); PG8_STAGE(PG8_SB(1, 0), b3, voffB); PG8_STAGE(PG8_SB(1, 1), b3 + hstep, voffB); PG8_STAGE(PG8_SA(1, 0), a3, voffA);
;             PG8_WAIT_V(8); PG8_WAIT_L(0); PG8_BAR; PG8_MMA(1, 0, At, B0); PG8_MMA(1, 1, At, B1); PG8_BAR; PG8_SCHED;
	ds_read_b128 v[146:149], v216 offset:32768
	ds_read_b128 v[150:153], v216 offset:33792
	ds_read_b128 v[154:157], v216 offset:34816
	ds_read_b128 v[158:161], v216 offset:35840
	ds_read_b128 v[162:165], v216 offset:49152
	ds_read_b128 v[166:169], v216 offset:50176
	ds_read_b128 v[170:173], v216 offset:51200
	ds_read_b128 v[174:177], v216 offset:52224
	s_add_u32 s22, s22, 0x40000
	s_addc_u32 s23, s23, 0
	s_mov_b32 m0, s36
	ds_read_b128 v[178:181], v144 offset:32768
	ds_read_b128 v[188:191], v144 offset:33792
	ds_read_b128 v[192:195], v144 offset:34816
	ds_read_b128 v[196:199], v144 offset:35840
	ds_read_b128 v[200:203], v144 offset:36864
	ds_read_b128 v[204:207], v144 offset:37888
	ds_read_b128 v[208:211], v144 offset:38912
	ds_read_b128 v[212:215], v144 offset:39936
	global_load_lds_dwordx4 v134, s[22:23]
	s_mov_b32 m0, s37
	s_add_u32 s98, s20, 0x80
	s_addc_u32 s99, s21, 0
	global_load_lds_dwordx4 v132, s[22:23]
	s_waitcnt vmcnt(8)
	s_waitcnt lgkmcnt(0)
	s_barrier
	s_setprio 1
	v_mfma_f32_16x16x32_bf16 v[126:129], v[146:149], v[178:181], v[126:129]
	v_mfma_f32_16x16x32_bf16 v[118:121], v[154:157], v[178:181], v[118:121]
	v_mfma_f32_16x16x32_bf16 v[110:113], v[146:149], v[192:195], v[110:113]
	v_mfma_f32_16x16x32_bf16 v[102:105], v[154:157], v[192:195], v[102:105]
	v_mfma_f32_16x16x32_bf16 v[94:97], v[146:149], v[200:203], v[94:97]
	v_mfma_f32_16x16x32_bf16 v[86:89], v[154:157], v[200:203], v[86:89]
	v_mfma_f32_16x16x32_bf16 v[78:81], v[146:149], v[208:211], v[78:81]
	v_mfma_f32_16x16x32_bf16 v[70:73], v[154:157], v[208:211], v[70:73]
	v_mfma_f32_16x16x32_bf16 v[126:129], v[150:153], v[188:191], v[126:129]
	v_mfma_f32_16x16x32_bf16 v[118:121], v[158:161], v[188:191], v[118:121]
	v_mfma_f32_16x16x32_bf16 v[110:113], v[150:153], v[196:199], v[110:113]
	v_mfma_f32_16x16x32_bf16 v[102:105], v[158:161], v[196:199], v[102:105]
	v_mfma_f32_16x16x32_bf16 v[94:97], v[150:153], v[204:207], v[94:97]
	v_mfma_f32_16x16x32_bf16 v[86:89], v[158:161], v[204:207], v[86:89]
	v_mfma_f32_16x16x32_bf16 v[78:81], v[150:153], v[212:215], v[78:81]
	v_mfma_f32_16x16x32_bf16 v[70:73], v[158:161], v[212:215], v[70:73]
	v_mfma_f32_16x16x32_bf16 v[122:125], v[162:165], v[178:181], v[122:125]
	v_mfma_f32_16x16x32_bf16 v[114:117], v[170:173], v[178:181], v[114:117]
	v_mfma_f32_16x16x32_bf16 v[106:109], v[162:165], v[192:195], v[106:109]
	v_mfma_f32_16x16x32_bf16 v[98:101], v[170:173], v[192:195], v[98:101]
	v_mfma_f32_16x16x32_bf16 v[90:93], v[162:165], v[200:203], v[90:93]
	v_mfma_f32_16x16x32_bf16 v[82:85], v[170:173], v[200:203], v[82:85]
	v_mfma_f32_16x16x32_bf16 v[74:77], v[162:165], v[208:211], v[74:77]
	v_mfma_f32_16x16x32_bf16 v[66:69], v[170:173], v[208:211], v[66:69]
	v_mfma_f32_16x16x32_bf16 v[122:125], v[166:169], v[188:191], v[122:125]
	v_mfma_f32_16x16x32_bf16 v[114:117], v[174:177], v[188:191], v[114:117]
	v_mfma_f32_16x16x32_bf16 v[106:109], v[166:169], v[196:199], v[106:109]
	v_mfma_f32_16x16x32_bf16 v[98:101], v[174:177], v[196:199], v[98:101]
	v_mfma_f32_16x16x32_bf16 v[90:93], v[166:169], v[204:207], v[90:93]
	v_mfma_f32_16x16x32_bf16 v[82:85], v[174:177], v[204:207], v[82:85]
	v_mfma_f32_16x16x32_bf16 v[74:77], v[166:169], v[212:215], v[74:77]
	v_mfma_f32_16x16x32_bf16 v[66:69], v[174:177], v[212:215], v[66:69]
	s_setprio 0
	s_barrier
	s_add_i32 m0, s33, 0x18000
	ds_read_b128 v[178:181], v144 offset:49152
	ds_read_b128 v[188:191], v144 offset:50176
	ds_read_b128 v[192:195], v144 offset:51200
	ds_read_b128 v[196:199], v144 offset:52224
	ds_read_b128 v[200:203], v144 offset:53248
	ds_read_b128 v[204:207], v144 offset:54272
	ds_read_b128 v[208:211], v144 offset:55296
	ds_read_b128 v[212:215], v144 offset:56320
	global_load_lds_dwordx4 v64, s[98:99]
	s_add_i32 m0, s33, 0x1a000
	s_add_u32 s20, s20, 0x40080
	s_addc_u32 s21, s21, 0
	global_load_lds_dwordx4 v130, s[98:99]
	s_add_i32 m0, s33, 0x1c000
	s_add_u32 s22, s22, 0xfffc0080
	s_addc_u32 s23, s23, -1
	global_load_lds_dwordx4 v64, s[20:21]
	s_add_i32 m0, s33, 0x1e000
	s_nop 0
	global_load_lds_dwordx4 v130, s[20:21]
	s_mov_b32 m0, s38
	s_nop 0
	global_load_lds_dwordx4 v134, s[22:23]
	s_mov_b32 m0, s39
	s_nop 0
	global_load_lds_dwordx4 v132, s[22:23]
	s_waitcnt vmcnt(8)
	s_waitcnt lgkmcnt(0)
	s_barrier
	s_setprio 1
	v_mfma_f32_16x16x32_bf16 v[60:63], v[146:149], v[178:181], v[60:63]
	v_mfma_f32_16x16x32_bf16 v[52:55], v[154:157], v[178:181], v[52:55]
	v_mfma_f32_16x16x32_bf16 v[44:47], v[146:149], v[192:195], v[44:47]
	v_mfma_f32_16x16x32_bf16 v[36:39], v[154:157], v[192:195], v[36:39]
	v_mfma_f32_16x16x32_bf16 v[28:31], v[146:149], v[200:203], v[28:31]
	v_mfma_f32_16x16x32_bf16 v[20:23], v[154:157], v[200:203], v[20:23]
	v_mfma_f32_16x16x32_bf16 v[12:15], v[146:149], v[208:211], v[12:15]
	v_mfma_f32_16x16x32_bf16 v[4:7], v[154:157], v[208:211], v[4:7]
	v_mfma_f32_16x16x32_bf16 v[60:63], v[150:153], v[188:191], v[60:63]
	v_mfma_f32_16x16x32_bf16 v[52:55], v[158:161], v[188:191], v[52:55]
	v_mfma_f32_16x16x32_bf16 v[44:47], v[150:153], v[196:199], v[44:47]
	v_mfma_f32_16x16x32_bf16 v[36:39], v[158:161], v[196:199], v[36:39]
	v_mfma_f32_16x16x32_bf16 v[28:31], v[150:153], v[204:207], v[28:31]
	v_mfma_f32_16x16x32_bf16 v[20:23], v[158:161], v[204:207], v[20:23]
	v_mfma_f32_16x16x32_bf16 v[12:15], v[150:153], v[212:215], v[12:15]
	v_mfma_f32_16x16x32_bf16 v[4:7], v[158:161], v[212:215], v[4:7]
	v_mfma_f32_16x16x32_bf16 v[56:59], v[162:165], v[178:181], v[56:59]
	v_mfma_f32_16x16x32_bf16 v[48:51], v[170:173], v[178:181], v[48:51]
	v_mfma_f32_16x16x32_bf16 v[40:43], v[162:165], v[192:195], v[40:43]
	v_mfma_f32_16x16x32_bf16 v[32:35], v[170:173], v[192:195], v[32:35]
	v_mfma_f32_16x16x32_bf16 v[24:27], v[162:165], v[200:203], v[24:27]
	v_mfma_f32_16x16x32_bf16 v[16:19], v[170:173], v[200:203], v[16:19]
	v_mfma_f32_16x16x32_bf16 v[8:11], v[162:165], v[208:211], v[8:11]
	v_mfma_f32_16x16x32_bf16 v[0:3], v[170:173], v[208:211], v[0:3]
	v_mfma_f32_16x16x32_bf16 v[56:59], v[166:169], v[188:191], v[56:59]
	v_mfma_f32_16x16x32_bf16 v[48:51], v[174:177], v[188:191], v[48:51]
	v_mfma_f32_16x16x32_bf16 v[40:43], v[166:169], v[196:199], v[40:43]
	v_mfma_f32_16x16x32_bf16 v[32:35], v[174:177], v[196:199], v[32:35]
	v_mfma_f32_16x16x32_bf16 v[24:27], v[166:169], v[204:207], v[24:27]
	v_mfma_f32_16x16x32_bf16 v[16:19], v[174:177], v[204:207], v[16:19]
	v_mfma_f32_16x16x32_bf16 v[8:11], v[166:169], v[212:215], v[8:11]
	v_mfma_f32_16x16x32_bf16 v[0:3], v[174:177], v[212:215], v[0:3]
	s_setprio 0
	s_barrier
	s_add_i32 s49, s49, 2
	s_add_u32 s18, s18, 0x100
	s_addc_u32 s19, s19, 0
	s_add_u32 s47, s47, 0x100
	s_addc_u32 s48, s48, 0
	s_cmp_gt_u32 s49, 13
	s_cbranch_scc0 .LBB0_65
	s_and_b64 vcc, exec, s[6:7]
	s_cbranch_vccz .LBB0_68
	s_barrier

; #define PG8_STAGE(bufoff, gbase, voff) do { _Pragma("unroll") for (int _i = 0; _i < 2; ++_i) \
;         __builtin_amdgcn_global_load_lds((const unsigned*)((const char*)(gbase) + (voff)[_i]), (PG8_LAS unsigned*)(lds + (bufoff) + ldsw + _i * 8192), 16, 0, 0); } while (0)
; #define PG8_LDA(dst, b, h) do { _Pragma("unroll") for (int m = 0; m < 4; ++m) _Pragma("unroll") for (int k = 0; k < 2; ++k) dst[m][k] = *(const PG8_LAS bf16x8*)(lds + PG8_SA(b, h) + aoff + m * 2048 + k * 1024); } while (0)
; #define PG8_LDB(dst, b, h) do { _Pragma("unroll") for (int n = 0; n < 2; ++n) _Pragma("unroll") for (int k = 0; k < 2; ++k) dst[n][k] = *(const PG8_LAS bf16x8*)(lds + PG8_SB(b, h) + boff + n * 2048 + k * 1024); } while (0)
; #define PG8_MMA(ai, bj, At, Bt) do { __builtin_amdgcn_s_setprio(1); _Pragma("unroll") for (int m = 0; m < 4; ++m) _Pragma("unroll") for (int n = 0; n < 2; ++n) _Pragma("unroll") for (int k = 0; k < 2; ++k) \
;         acc[ai][bj][m][n] = __builtin_amdgcn_mfma_f32_16x16x32_bf16(Bt[n][k], At[m][k], acc[ai][bj][m][n], 0, 0, 0); __builtin_amdgcn_s_setprio(0); } while (0)
; #define PG8_WAIT_V(n) asm volatile("s_waitcnt vmcnt(" #n ")" ::: "memory")
; #define PG8_WAIT_L(n) asm volatile("s_waitcnt lgkmcnt(" #n ")" ::: "memory")
; template <class Epi, class Sched, bool ALIGN_EPI = false, bool SP2 = false>
; __device__ __forceinline__ void gemm_phase(PG8_LAS unsigned char* lds, const Gemm g, const Sched& S, const Epi& E) {
;     ...
;             const bool last = (t == nt - 2);
;             const char* a1 = cA + (size_t)(t + 1) * kstep;
;             const char* a2 = last ? nA : cA + (size_t)(t + 2) * kstep; const char* b2 = last ? nB : cB + (size_t)(t + 2) * kstep;
;             const char* a3 = a2 + kstep; const char* b3 = b2 + kstep;
;             if (last && has_next) S.a_ready(nxt);
;             if constexpr (SP2) {
;             PG8_LDB(B0, 0, 0); PG8_LDB(B1, 0, 1); PG8_SCHED; PG8_LDA(At, 0, 0); PG8_STAGE(PG8_SA(1, 1), a1 + hstep, voffA);
;             PG8_WAIT_V(8); PG8_WAIT_L(0); PG8_BAR; PG8_MMA(0, 0, At, B0); PG8_MMA(0, 1, At, B1); PG8_BAR; PG8_SCHED;
;             PG8_LDA(At, 0, 1); PG8_STAGE(PG8_SB(0, 0), b2, voffB); PG8_STAGE(PG8_SB(0, 1), b2 + hstep, voffB); PG8_STAGE(PG8_SA(0, 0), a2, voffA);
;             PG8_WAIT_V(8); PG8_WAIT_L(0); PG8_BAR; PG8_MMA(1, 0, At, B0); PG8_MMA(1, 1, At, B1); PG8_BAR; PG8_SCHED;
.LBB0_97:
	s_add_i32 s46, s20, 2
	s_add_u32 s47, s18, 0x80
	s_addc_u32 s21, s19, 0
	s_add_i32 s54, 0, 0x10000
	s_cmp_eq_u32 s41, s20
	s_cselect_b32 s21, s1, s21
	s_cselect_b32 s20, s0, s47
	v_add_u32_e32 v64, s54, v231
	s_cselect_b32 s53, s17, s23
	s_cselect_b32 s52, s16, s22
	s_add_i32 s47, 0, 0x14000
	ds_read_b128 v[56:59], v64
	ds_read_b128 v[72:75], v64 offset:1024
	ds_read_b128 v[76:79], v64 offset:2048
	ds_read_b128 v[80:83], v64 offset:3072
	v_add_u32_e32 v64, s47, v231
	ds_read_b128 v[84:87], v64
	ds_read_b128 v[88:91], v64 offset:1024
	ds_read_b128 v[92:95], v64 offset:2048
	ds_read_b128 v[100:103], v64 offset:3072
	v_lshl_add_u64 v[66:67], s[18:19], 0, v[196:197]
	s_add_i32 m0, s33, 0xc000
	ds_read_b128 v[116:119], v233
	ds_read_b128 v[120:123], v233 offset:1024
	ds_read_b128 v[140:143], v233 offset:2048
	ds_read_b128 v[144:147], v233 offset:3072
	ds_read_b128 v[180:183], v233 offset:4096
	ds_read_b128 v[200:203], v233 offset:5120
	ds_read_b128 v[204:207], v233 offset:6144
	ds_read_b128 v[208:211], v233 offset:7168
	global_load_lds_dwordx4 v[66:67], off
	v_lshl_add_u64 v[66:67], s[18:19], 0, v[198:199]
	s_add_i32 m0, s33, 0xe000
	s_nop 0
	global_load_lds_dwordx4 v[66:67], off
	s_waitcnt vmcnt(8)
	s_waitcnt lgkmcnt(0)
	s_barrier
	s_setprio 1
	v_mfma_f32_16x16x32_bf16 v[176:179], v[56:59], v[116:119], v[176:179]
	v_mfma_f32_16x16x32_bf16 v[172:175], v[76:79], v[116:119], v[172:175]
	v_mfma_f32_16x16x32_bf16 v[160:163], v[56:59], v[140:143], v[160:163]
	v_mfma_f32_16x16x32_bf16 v[156:159], v[76:79], v[140:143], v[156:159]
	v_mfma_f32_16x16x32_bf16 v[136:139], v[56:59], v[180:183], v[136:139]
	v_mfma_f32_16x16x32_bf16 v[132:135], v[76:79], v[180:183], v[132:135]
	v_mfma_f32_16x16x32_bf16 v[112:115], v[56:59], v[204:207], v[112:115]
	v_mfma_f32_16x16x32_bf16 v[108:111], v[76:79], v[204:207], v[108:111]
	v_mfma_f32_16x16x32_bf16 v[176:179], v[72:75], v[120:123], v[176:179]
	v_mfma_f32_16x16x32_bf16 v[172:175], v[80:83], v[120:123], v[172:175]
	v_mfma_f32_16x16x32_bf16 v[160:163], v[72:75], v[144:147], v[160:163]
	v_mfma_f32_16x16x32_bf16 v[156:159], v[80:83], v[144:147], v[156:159]
	v_mfma_f32_16x16x32_bf16 v[136:139], v[72:75], v[200:203], v[136:139]
	v_mfma_f32_16x16x32_bf16 v[132:135], v[80:83], v[200:203], v[132:135]
	v_mfma_f32_16x16x32_bf16 v[112:115], v[72:75], v[208:211], v[112:115]
	v_mfma_f32_16x16x32_bf16 v[108:111], v[80:83], v[208:211], v[108:111]
	v_mfma_f32_16x16x32_bf16 v[168:171], v[84:87], v[116:119], v[168:171]
	v_mfma_f32_16x16x32_bf16 v[116:119], v[92:95], v[116:119], v[164:167]
	v_mfma_f32_16x16x32_bf16 v[128:131], v[84:87], v[180:183], v[128:131]
	v_mfma_f32_16x16x32_bf16 v[124:127], v[92:95], v[180:183], v[124:127]
	v_mfma_f32_16x16x32_bf16 v[104:107], v[84:87], v[204:207], v[104:107]
	v_mfma_f32_16x16x32_bf16 v[96:99], v[92:95], v[204:207], v[96:99]
	v_mfma_f32_16x16x32_bf16 v[168:171], v[88:91], v[120:123], v[168:171]
	v_mfma_f32_16x16x32_bf16 v[116:119], v[100:103], v[120:123], v[116:119]
	v_mfma_f32_16x16x32_bf16 v[120:123], v[84:87], v[140:143], v[152:155]
	v_mfma_f32_16x16x32_bf16 v[140:143], v[92:95], v[140:143], v[148:151]
	v_mfma_f32_16x16x32_bf16 v[128:131], v[88:91], v[200:203], v[128:131]
	v_mfma_f32_16x16x32_bf16 v[124:127], v[100:103], v[200:203], v[124:127]
	v_mfma_f32_16x16x32_bf16 v[104:107], v[88:91], v[208:211], v[104:107]
	v_mfma_f32_16x16x32_bf16 v[96:99], v[100:103], v[208:211], v[96:99]
	v_mfma_f32_16x16x32_bf16 v[120:123], v[88:91], v[144:147], v[120:123]
	v_mfma_f32_16x16x32_bf16 v[140:143], v[100:103], v[144:147], v[140:143]
	s_setprio 0
	s_barrier
	s_add_i32 s54, s54, s27
	v_lshl_add_u64 v[234:235], s[52:53], 0, v[190:191]
	s_mov_b32 m0, s54
	ds_read_b128 v[144:147], v233 offset:16384
	ds_read_b128 v[148:151], v233 offset:17408
	ds_read_b128 v[152:155], v233 offset:18432
	ds_read_b128 v[164:167], v233 offset:19456
	ds_read_b128 v[180:183], v233 offset:20480
	ds_read_b128 v[200:203], v233 offset:21504
	ds_read_b128 v[204:207], v233 offset:22528
	ds_read_b128 v[208:211], v233 offset:23552
	global_load_lds_dwordx4 v[234:235], off
	s_add_i32 m0, s54, 0x2000
	v_lshl_add_u64 v[236:237], s[52:53], 0, v[194:195]
	s_add_u32 s52, s52, s2
	s_addc_u32 s53, s53, 0
	s_add_i32 s47, s47, s27
	global_load_lds_dwordx4 v[236:237], off
	v_lshl_add_u64 v[238:239], s[52:53], 0, v[190:191]
	s_mov_b32 m0, s47
	v_lshl_add_u64 v[240:241], s[52:53], 0, v[194:195]
	global_load_lds_dwordx4 v[238:239], off
	s_add_i32 m0, s47, 0x2000
	v_lshl_add_u64 v[242:243], s[20:21], 0, v[188:189]
	global_load_lds_dwordx4 v[240:241], off
	s_mov_b32 m0, s33
	v_lshl_add_u64 v[244:245], s[20:21], 0, v[192:193]
	global_load_lds_dwordx4 v[242:243], off
	s_mov_b32 m0, s34
	s_nop 0
	global_load_lds_dwordx4 v[244:245], off
	s_waitcnt vmcnt(8)
	s_waitcnt lgkmcnt(0)
	s_barrier
; #define PG8_STAGE(bufoff, gbase, voff) do { _Pragma("unroll") for (int _i = 0; _i < 2; ++_i) \
;         __builtin_amdgcn_global_load_lds((const unsigned*)((const char*)(gbase) + (voff)[_i]), (PG8_LAS unsigned*)(lds + (bufoff) + ldsw + _i * 8192), 16, 0, 0); } while (0)
; #define PG8_LDA(dst, b, h) do { _Pragma("unroll") for (int m = 0; m < 4; ++m) _Pragma("unroll") for (int k = 0; k < 2; ++k) dst[m][k] = *(const PG8_LAS bf16x8*)(lds + PG8_SA(b, h) + aoff + m * 2048 + k * 1024); } while (0)
; #define PG8_LDB(dst, b, h) do { _Pragma("unroll") for (int n = 0; n < 2; ++n) _Pragma("unroll") for (int k = 0; k < 2; ++k) dst[n][k] = *(const PG8_LAS bf16x8*)(lds + PG8_SB(b, h) + boff + n * 2048 + k * 1024); } while (0)
; #define PG8_MMA(ai, bj, At, Bt) do { __builtin_amdgcn_s_setprio(1); _Pragma("unroll") for (int m = 0; m < 4; ++m) _Pragma("unroll") for (int n = 0; n < 2; ++n) _Pragma("unroll") for (int k = 0; k < 2; ++k) \
;         acc[ai][bj][m][n] = __builtin_amdgcn_mfma_f32_16x16x32_bf16(Bt[n][k], At[m][k], acc[ai][bj][m][n], 0, 0, 0); __builtin_amdgcn_s_setprio(0); } while (0)
; #define PG8_WAIT_V(n) asm volatile("s_waitcnt vmcnt(" #n ")" ::: "memory")
; #define PG8_WAIT_L(n) asm volatile("s_waitcnt lgkmcnt(" #n ")" ::: "memory")
; #define PG8_BAR __builtin_amdgcn_s_barrier()
; #define PG8_SCHED __builtin_amdgcn_sched_barrier(0)
; template <class Epi, class Sched, bool ALIGN_EPI = false, bool SP2 = false>
; __device__ __forceinline__ void gemm_phase(PG8_LAS unsigned char* lds, const Gemm g, const Sched& S, const Epi& E) {
;     ...
;             PG8_WAIT_V(8); PG8_WAIT_L(0); PG8_BAR; PG8_MMA(1, 0, At, B0); PG8_MMA(1, 1, At, B1); PG8_BAR; PG8_SCHED;
;             PG8_LDB(B0, 1, 0); PG8_LDB(B1, 1, 1); PG8_SCHED; PG8_LDA(At, 1, 0); PG8_STAGE(PG8_SA(0, 1), a2 + hstep, voffA);
;             PG8_WAIT_V(8); PG8_WAIT_L(0); PG8_BAR; PG8_MMA(0, 0, At, B0); PG8_MMA(0, 1, At, B1); PG8_BAR; PG8_SCHED;
	s_setprio 1
	v_mfma_f32_16x16x32_bf16 v[66:69], v[56:59], v[144:147], v[68:71]
	v_mfma_f32_16x16x32_bf16 v[60:63], v[76:79], v[144:147], v[60:63]
	v_mfma_f32_16x16x32_bf16 v[44:47], v[56:59], v[152:155], v[44:47]
	v_mfma_f32_16x16x32_bf16 v[40:43], v[76:79], v[152:155], v[40:43]
	v_mfma_f32_16x16x32_bf16 v[28:31], v[56:59], v[180:183], v[28:31]
	v_mfma_f32_16x16x32_bf16 v[24:27], v[76:79], v[180:183], v[24:27]
	v_mfma_f32_16x16x32_bf16 v[12:15], v[56:59], v[204:207], v[12:15]
	v_mfma_f32_16x16x32_bf16 v[8:11], v[76:79], v[204:207], v[8:11]
	v_mfma_f32_16x16x32_bf16 v[66:69], v[72:75], v[148:151], v[66:69]
	v_mfma_f32_16x16x32_bf16 v[60:63], v[80:83], v[148:151], v[60:63]
	v_mfma_f32_16x16x32_bf16 v[44:47], v[72:75], v[164:167], v[44:47]
	v_mfma_f32_16x16x32_bf16 v[40:43], v[80:83], v[164:167], v[40:43]
	v_mfma_f32_16x16x32_bf16 v[28:31], v[72:75], v[200:203], v[28:31]
	v_mfma_f32_16x16x32_bf16 v[24:27], v[80:83], v[200:203], v[24:27]
	v_mfma_f32_16x16x32_bf16 v[12:15], v[72:75], v[208:211], v[12:15]
	v_mfma_f32_16x16x32_bf16 v[8:11], v[80:83], v[208:211], v[8:11]
	v_mfma_f32_16x16x32_bf16 v[52:55], v[84:87], v[144:147], v[52:55]
	v_mfma_f32_16x16x32_bf16 v[48:51], v[92:95], v[144:147], v[48:51]
	v_mfma_f32_16x16x32_bf16 v[36:39], v[84:87], v[152:155], v[36:39]
	v_mfma_f32_16x16x32_bf16 v[32:35], v[92:95], v[152:155], v[32:35]
	v_mfma_f32_16x16x32_bf16 v[20:23], v[84:87], v[180:183], v[20:23]
	v_mfma_f32_16x16x32_bf16 v[16:19], v[92:95], v[180:183], v[16:19]
	v_mfma_f32_16x16x32_bf16 v[4:7], v[84:87], v[204:207], v[4:7]
	v_mfma_f32_16x16x32_bf16 v[0:3], v[92:95], v[204:207], v[0:3]
	v_mfma_f32_16x16x32_bf16 v[52:55], v[88:91], v[148:151], v[52:55]
	v_mfma_f32_16x16x32_bf16 v[48:51], v[100:103], v[148:151], v[48:51]
	v_mfma_f32_16x16x32_bf16 v[36:39], v[88:91], v[164:167], v[36:39]
	v_mfma_f32_16x16x32_bf16 v[32:35], v[100:103], v[164:167], v[32:35]
	v_mfma_f32_16x16x32_bf16 v[20:23], v[88:91], v[200:203], v[20:23]
	v_mfma_f32_16x16x32_bf16 v[16:19], v[100:103], v[200:203], v[16:19]
	v_mfma_f32_16x16x32_bf16 v[4:7], v[88:91], v[208:211], v[4:7]
	v_mfma_f32_16x16x32_bf16 v[0:3], v[100:103], v[208:211], v[0:3]
	s_setprio 0
	s_barrier
	s_add_i32 s47, 0, 0x18000
	v_add_u32_e32 v64, s47, v231
	s_add_i32 s52, 0, 0x1c000
	ds_read_b128 v[56:59], v64
	ds_read_b128 v[72:75], v64 offset:1024
	ds_read_b128 v[76:79], v64 offset:2048
	ds_read_b128 v[80:83], v64 offset:3072
	v_add_u32_e32 v64, s52, v231
	ds_read_b128 v[84:87], v64
	ds_read_b128 v[88:91], v64 offset:1024
	ds_read_b128 v[92:95], v64 offset:2048
	ds_read_b128 v[100:103], v64 offset:3072
	s_add_u32 s20, s20, s2
	s_addc_u32 s21, s21, 0
	s_mov_b32 m0, s35
	v_lshl_add_u64 v[70:71], s[20:21], 0, v[188:189]
	ds_read_b128 v[144:147], v233 offset:32768
	ds_read_b128 v[148:151], v233 offset:33792
	ds_read_b128 v[180:183], v233 offset:34816
	ds_read_b128 v[200:203], v233 offset:35840
	ds_read_b128 v[204:207], v233 offset:36864
	ds_read_b128 v[208:211], v233 offset:37888
	ds_read_b128 v[212:215], v233 offset:38912
	ds_read_b128 v[216:219], v233 offset:39936
	global_load_lds_dwordx4 v[70:71], off
	v_lshl_add_u64 v[70:71], s[20:21], 0, v[192:193]
	s_mov_b32 m0, s36
	s_nop 0
	global_load_lds_dwordx4 v[70:71], off
	s_waitcnt vmcnt(8)
	s_waitcnt lgkmcnt(0)
	s_barrier
	s_setprio 1
	v_mfma_f32_16x16x32_bf16 v[152:155], v[56:59], v[144:147], v[176:179]
	v_mfma_f32_16x16x32_bf16 v[176:179], v[72:75], v[148:151], v[152:155]
	v_mfma_f32_16x16x32_bf16 v[152:155], v[76:79], v[144:147], v[172:175]
	v_mfma_f32_16x16x32_bf16 v[172:175], v[80:83], v[148:151], v[152:155]
	v_mfma_f32_16x16x32_bf16 v[152:155], v[56:59], v[180:183], v[160:163]
	v_mfma_f32_16x16x32_bf16 v[160:163], v[72:75], v[200:203], v[152:155]
	v_mfma_f32_16x16x32_bf16 v[152:155], v[76:79], v[180:183], v[156:159]
	v_mfma_f32_16x16x32_bf16 v[136:139], v[56:59], v[204:207], v[136:139]
	v_mfma_f32_16x16x32_bf16 v[132:135], v[76:79], v[204:207], v[132:135]
	v_mfma_f32_16x16x32_bf16 v[112:115], v[56:59], v[212:215], v[112:115]
	v_mfma_f32_16x16x32_bf16 v[108:111], v[76:79], v[212:215], v[108:111]
	v_mfma_f32_16x16x32_bf16 v[156:159], v[80:83], v[200:203], v[152:155]
	v_mfma_f32_16x16x32_bf16 v[136:139], v[72:75], v[208:211], v[136:139]
	v_mfma_f32_16x16x32_bf16 v[132:135], v[80:83], v[208:211], v[132:135]
	v_mfma_f32_16x16x32_bf16 v[112:115], v[72:75], v[216:219], v[112:115]
	v_mfma_f32_16x16x32_bf16 v[108:111], v[80:83], v[216:219], v[108:111]
	v_mfma_f32_16x16x32_bf16 v[116:119], v[92:95], v[144:147], v[116:119]
	v_mfma_f32_16x16x32_bf16 v[152:155], v[84:87], v[144:147], v[168:171]
	v_mfma_f32_16x16x32_bf16 v[164:167], v[100:103], v[148:151], v[116:119]
	v_mfma_f32_16x16x32_bf16 v[116:119], v[84:87], v[180:183], v[120:123]
	v_mfma_f32_16x16x32_bf16 v[168:171], v[88:91], v[148:151], v[152:155]
	v_mfma_f32_16x16x32_bf16 v[152:155], v[88:91], v[200:203], v[116:119]
	v_mfma_f32_16x16x32_bf16 v[116:119], v[92:95], v[180:183], v[140:143]
	v_mfma_f32_16x16x32_bf16 v[148:151], v[100:103], v[200:203], v[116:119]
	v_mfma_f32_16x16x32_bf16 v[116:119], v[84:87], v[204:207], v[128:131]
	v_mfma_f32_16x16x32_bf16 v[128:131], v[88:91], v[208:211], v[116:119]
	v_mfma_f32_16x16x32_bf16 v[116:119], v[92:95], v[204:207], v[124:127]
	v_mfma_f32_16x16x32_bf16 v[104:107], v[84:87], v[212:215], v[104:107]
	v_mfma_f32_16x16x32_bf16 v[96:99], v[92:95], v[212:215], v[96:99]
	v_mfma_f32_16x16x32_bf16 v[124:127], v[100:103], v[208:211], v[116:119]
	v_mfma_f32_16x16x32_bf16 v[104:107], v[88:91], v[216:219], v[104:107]
	v_mfma_f32_16x16x32_bf16 v[96:99], v[100:103], v[216:219], v[96:99]
	s_setprio 0
	s_barrier
; #define PG8_STAGE(bufoff, gbase, voff) do { _Pragma("unroll") for (int _i = 0; _i < 2; ++_i) \
;         __builtin_amdgcn_global_load_lds((const unsigned*)((const char*)(gbase) + (voff)[_i]), (PG8_LAS unsigned*)(lds + (bufoff) + ldsw + _i * 8192), 16, 0, 0); } while (0)
; #define PG8_LDA(dst, b, h) do { _Pragma("unroll") for (int m = 0; m < 4; ++m) _Pragma("unroll") for (int k = 0; k < 2; ++k) dst[m][k] = *(const PG8_LAS bf16x8*)(lds + PG8_SA(b, h) + aoff + m * 2048 + k * 1024); } while (0)
; #define PG8_MMA(ai, bj, At, Bt) do { __builtin_amdgcn_s_setprio(1); _Pragma("unroll") for (int m = 0; m < 4; ++m) _Pragma("unroll") for (int n = 0; n < 2; ++n) _Pragma("unroll") for (int k = 0; k < 2; ++k) \
;         acc[ai][bj][m][n] = __builtin_amdgcn_mfma_f32_16x16x32_bf16(Bt[n][k], At[m][k], acc[ai][bj][m][n], 0, 0, 0); __builtin_amdgcn_s_setprio(0); } while (0)
; #define PG8_WAIT_V(n) asm volatile("s_waitcnt vmcnt(" #n ")" ::: "memory")
; #define PG8_WAIT_L(n) asm volatile("s_waitcnt lgkmcnt(" #n ")" ::: "memory")
; #define PG8_BAR __builtin_amdgcn_s_barrier()
; #define PG8_SCHED __builtin_amdgcn_sched_barrier(0)
; template <class Epi, class Sched, bool ALIGN_EPI = false, bool SP2 = false>
; __device__ __forceinline__ void gemm_phase(PG8_LAS unsigned char* lds, const Gemm g, const Sched& S, const Epi& E) {
;     ...
;             PG8_LDA(At, 1, 1); PG8_STAGE(PG8_SB(1, 0), b3, voffB); PG8_STAGE(PG8_SB(1, 1), b3 + hstep, voffB); PG8_STAGE(PG8_SA(1, 0), a3, voffA);
;             PG8_WAIT_V(8); PG8_WAIT_L(0); PG8_BAR; PG8_MMA(1, 0, At, B0); PG8_MMA(1, 1, At, B1); PG8_BAR; PG8_SCHED;
	s_add_i32 s20, s47, s27
	v_lshl_add_u64 v[70:71], v[234:235], 0, s[56:57]
	s_mov_b32 m0, s20
	ds_read_b128 v[116:119], v233 offset:49152
	ds_read_b128 v[120:123], v233 offset:50176
	ds_read_b128 v[140:143], v233 offset:51200
	ds_read_b128 v[144:147], v233 offset:52224
	ds_read_b128 v[180:183], v233 offset:53248
	ds_read_b128 v[200:203], v233 offset:54272
	ds_read_b128 v[204:207], v233 offset:55296
	ds_read_b128 v[208:211], v233 offset:56320
	global_load_lds_dwordx4 v[70:71], off
	v_lshl_add_u64 v[70:71], v[236:237], 0, s[56:57]
	s_add_i32 m0, s20, 0x2000
	s_add_i32 s20, s52, s27
	global_load_lds_dwordx4 v[70:71], off
	v_lshl_add_u64 v[70:71], v[238:239], 0, s[56:57]
	s_mov_b32 m0, s20
	s_nop 0
	global_load_lds_dwordx4 v[70:71], off
	v_lshl_add_u64 v[70:71], v[240:241], 0, s[56:57]
	s_add_i32 m0, s20, 0x2000
	s_nop 0
	global_load_lds_dwordx4 v[70:71], off
	v_lshl_add_u64 v[70:71], v[242:243], 0, s[56:57]
	s_mov_b32 m0, s39
	s_nop 0
	global_load_lds_dwordx4 v[70:71], off
	v_lshl_add_u64 v[70:71], v[244:245], 0, s[56:57]
	s_mov_b32 m0, s40
	s_nop 0
	global_load_lds_dwordx4 v[70:71], off
	s_waitcnt vmcnt(8)
	s_waitcnt lgkmcnt(0)
	s_barrier
	s_setprio 1
	v_mfma_f32_16x16x32_bf16 v[66:69], v[56:59], v[116:119], v[66:69]
	v_mfma_f32_16x16x32_bf16 v[60:63], v[76:79], v[116:119], v[60:63]
	v_mfma_f32_16x16x32_bf16 v[44:47], v[56:59], v[140:143], v[44:47]
	v_mfma_f32_16x16x32_bf16 v[40:43], v[76:79], v[140:143], v[40:43]
	v_mfma_f32_16x16x32_bf16 v[28:31], v[56:59], v[180:183], v[28:31]
	v_mfma_f32_16x16x32_bf16 v[24:27], v[76:79], v[180:183], v[24:27]
	v_mfma_f32_16x16x32_bf16 v[12:15], v[56:59], v[204:207], v[12:15]
	v_mfma_f32_16x16x32_bf16 v[8:11], v[76:79], v[204:207], v[8:11]
	v_mfma_f32_16x16x32_bf16 v[68:71], v[72:75], v[120:123], v[66:69]
	v_mfma_f32_16x16x32_bf16 v[60:63], v[80:83], v[120:123], v[60:63]
	v_mfma_f32_16x16x32_bf16 v[44:47], v[72:75], v[144:147], v[44:47]
	v_mfma_f32_16x16x32_bf16 v[40:43], v[80:83], v[144:147], v[40:43]
	v_mfma_f32_16x16x32_bf16 v[28:31], v[72:75], v[200:203], v[28:31]
	v_mfma_f32_16x16x32_bf16 v[24:27], v[80:83], v[200:203], v[24:27]
	v_mfma_f32_16x16x32_bf16 v[12:15], v[72:75], v[208:211], v[12:15]
	v_mfma_f32_16x16x32_bf16 v[8:11], v[80:83], v[208:211], v[8:11]
	v_mfma_f32_16x16x32_bf16 v[52:55], v[84:87], v[116:119], v[52:55]
	v_mfma_f32_16x16x32_bf16 v[48:51], v[92:95], v[116:119], v[48:51]
	v_mfma_f32_16x16x32_bf16 v[36:39], v[84:87], v[140:143], v[36:39]
	v_mfma_f32_16x16x32_bf16 v[32:35], v[92:95], v[140:143], v[32:35]
	v_mfma_f32_16x16x32_bf16 v[20:23], v[84:87], v[180:183], v[20:23]
	v_mfma_f32_16x16x32_bf16 v[16:19], v[92:95], v[180:183], v[16:19]
	v_mfma_f32_16x16x32_bf16 v[4:7], v[84:87], v[204:207], v[4:7]
	v_mfma_f32_16x16x32_bf16 v[0:3], v[92:95], v[204:207], v[0:3]
	v_mfma_f32_16x16x32_bf16 v[52:55], v[88:91], v[120:123], v[52:55]
	v_mfma_f32_16x16x32_bf16 v[48:51], v[100:103], v[120:123], v[48:51]
	v_mfma_f32_16x16x32_bf16 v[36:39], v[88:91], v[144:147], v[36:39]
	v_mfma_f32_16x16x32_bf16 v[32:35], v[100:103], v[144:147], v[32:35]
	v_mfma_f32_16x16x32_bf16 v[20:23], v[88:91], v[200:203], v[20:23]
	v_mfma_f32_16x16x32_bf16 v[16:19], v[100:103], v[200:203], v[16:19]
	v_mfma_f32_16x16x32_bf16 v[4:7], v[88:91], v[208:211], v[4:7]
	v_mfma_f32_16x16x32_bf16 v[0:3], v[100:103], v[208:211], v[0:3]
	s_setprio 0
	s_barrier
	s_add_u32 s18, s18, 0x100
	s_addc_u32 s19, s19, 0
	s_add_u32 s22, s22, 0x100
	s_addc_u32 s23, s23, 0
	s_cmp_ge_u32 s46, s38
	s_mov_b32 s20, s46
	s_cbranch_scc0 .LBB0_97
	s_and_b64 vcc, exec, s[12:13]
	s_cbranch_vccz .LBB0_100
	s_barrier

; #define PG8_STAGE(bufoff, gbase, voff) do { _Pragma("unroll") for (int _i = 0; _i < 2; ++_i) \
;         __builtin_amdgcn_global_load_lds((const unsigned*)((const char*)(gbase) + (voff)[_i]), (PG8_LAS unsigned*)(lds + (bufoff) + ldsw + _i * 8192), 16, 0, 0); } while (0)
; #define PG8_LDA(dst, b, h) do { _Pragma("unroll") for (int m = 0; m < 4; ++m) _Pragma("unroll") for (int k = 0; k < 2; ++k) dst[m][k] = *(const PG8_LAS bf16x8*)(lds + PG8_SA(b, h) + aoff + m * 2048 + k * 1024); } while (0)
; #define PG8_LDB(dst, b, h) do { _Pragma("unroll") for (int n = 0; n < 2; ++n) _Pragma("unroll") for (int k = 0; k < 2; ++k) dst[n][k] = *(const PG8_LAS bf16x8*)(lds + PG8_SB(b, h) + boff + n * 2048 + k * 1024); } while (0)
; #define PG8_MMA(ai, bj, At, Bt) do { __builtin_amdgcn_s_setprio(1); _Pragma("unroll") for (int m = 0; m < 4; ++m) _Pragma("unroll") for (int n = 0; n < 2; ++n) _Pragma("unroll") for (int k = 0; k < 2; ++k) \
;         acc[ai][bj][m][n] = __builtin_amdgcn_mfma_f32_16x16x32_bf16(Bt[n][k], At[m][k], acc[ai][bj][m][n], 0, 0, 0); __builtin_amdgcn_s_setprio(0); } while (0)
; #define PG8_WAIT_V(n) asm volatile("s_waitcnt vmcnt(" #n ")" ::: "memory")
; #define PG8_WAIT_L(n) asm volatile("s_waitcnt lgkmcnt(" #n ")" ::: "memory")
; template <class Epi, class Sched, bool ALIGN_EPI = false, bool SP2 = false>
; __device__ __forceinline__ void gemm_phase(PG8_LAS unsigned char* lds, const Gemm g, const Sched& S, const Epi& E) {
;     ...
;             const bool last = (t == nt - 2);
;             const char* a1 = cA + (size_t)(t + 1) * kstep;
;             const char* a2 = last ? nA : cA + (size_t)(t + 2) * kstep; const char* b2 = last ? nB : cB + (size_t)(t + 2) * kstep;
;             const char* a3 = a2 + kstep; const char* b3 = b2 + kstep;
;             if (last && has_next) S.a_ready(nxt);
;             if constexpr (SP2) {
;             PG8_LDB(B0, 0, 0); PG8_LDB(B1, 0, 1); PG8_SCHED; PG8_LDA(At, 0, 0); PG8_STAGE(PG8_SA(1, 1), a1 + hstep, voffA);
;             PG8_WAIT_V(8); PG8_WAIT_L(0); PG8_BAR; PG8_MMA(0, 0, At, B0); PG8_MMA(0, 1, At, B1); PG8_BAR; PG8_SCHED;
;             PG8_LDA(At, 0, 1); PG8_STAGE(PG8_SB(0, 0), b2, voffB); PG8_STAGE(PG8_SB(0, 1), b2 + hstep, voffB); PG8_STAGE(PG8_SA(0, 0), a2, voffA);
;             PG8_WAIT_V(8); PG8_WAIT_L(0); PG8_BAR; PG8_MMA(1, 0, At, B0); PG8_MMA(1, 1, At, B1); PG8_BAR; PG8_SCHED;
.LBB0_252:
	s_add_u32 s18, s16, 0xfffc0080
	s_addc_u32 s19, s17, -1
	s_add_i32 s47, 0, 0x10000
	s_cmp_eq_u32 s46, 12
	s_cselect_b32 s21, s9, s19
	s_cselect_b32 s20, s40, s18
	v_add_u32_e32 v64, s47, v152
	s_cselect_b32 s19, s7, s45
	s_cselect_b32 s18, s41, s44
	s_add_i32 s50, 0, 0x14000
	ds_read_b128 v[142:145], v64
	ds_read_b128 v[158:161], v64 offset:1024
	ds_read_b128 v[162:165], v64 offset:2048
	ds_read_b128 v[166:169], v64 offset:3072
	v_add_u32_e32 v64, s50, v152
	ds_read_b128 v[170:173], v64
	ds_read_b128 v[174:177], v64 offset:1024
	ds_read_b128 v[178:181], v64 offset:2048
	ds_read_b128 v[188:191], v64 offset:3072
	v_lshl_add_u64 v[146:147], s[16:17], 0, v[138:139]
	s_add_i32 m0, s28, 0xc000
	ds_read_b128 v[192:195], v156
	ds_read_b128 v[196:199], v156 offset:1024
	ds_read_b128 v[200:203], v156 offset:2048
	ds_read_b128 v[204:207], v156 offset:3072
	ds_read_b128 v[208:211], v156 offset:4096
	ds_read_b128 v[212:215], v156 offset:5120
	ds_read_b128 v[216:219], v156 offset:6144
	ds_read_b128 v[230:233], v156 offset:7168
	global_load_lds_dwordx4 v[146:147], off
	v_lshl_add_u64 v[146:147], s[16:17], 0, v[140:141]
	s_add_i32 m0, s28, 0xe000
	s_nop 0
	global_load_lds_dwordx4 v[146:147], off
	s_waitcnt vmcnt(8)
	s_waitcnt lgkmcnt(0)
	s_barrier
	s_setprio 1
	v_mfma_f32_16x16x32_bf16 v[126:129], v[142:145], v[192:195], v[126:129]
	v_mfma_f32_16x16x32_bf16 v[122:125], v[162:165], v[192:195], v[122:125]
	v_mfma_f32_16x16x32_bf16 v[114:117], v[142:145], v[200:203], v[114:117]
	v_mfma_f32_16x16x32_bf16 v[106:109], v[162:165], v[200:203], v[106:109]
	v_mfma_f32_16x16x32_bf16 v[102:105], v[142:145], v[208:211], v[102:105]
	v_mfma_f32_16x16x32_bf16 v[94:97], v[162:165], v[208:211], v[94:97]
	v_mfma_f32_16x16x32_bf16 v[82:85], v[142:145], v[216:219], v[82:85]
	v_mfma_f32_16x16x32_bf16 v[74:77], v[162:165], v[216:219], v[74:77]
	v_mfma_f32_16x16x32_bf16 v[126:129], v[158:161], v[196:199], v[126:129]
	v_mfma_f32_16x16x32_bf16 v[122:125], v[166:169], v[196:199], v[122:125]
	v_mfma_f32_16x16x32_bf16 v[114:117], v[158:161], v[204:207], v[114:117]
	v_mfma_f32_16x16x32_bf16 v[106:109], v[166:169], v[204:207], v[106:109]
	v_mfma_f32_16x16x32_bf16 v[102:105], v[158:161], v[212:215], v[102:105]
	v_mfma_f32_16x16x32_bf16 v[94:97], v[166:169], v[212:215], v[94:97]
	v_mfma_f32_16x16x32_bf16 v[82:85], v[158:161], v[230:233], v[82:85]
	v_mfma_f32_16x16x32_bf16 v[74:77], v[166:169], v[230:233], v[74:77]
	v_mfma_f32_16x16x32_bf16 v[118:121], v[170:173], v[192:195], v[118:121]
	v_mfma_f32_16x16x32_bf16 v[110:113], v[178:181], v[192:195], v[110:113]
	v_mfma_f32_16x16x32_bf16 v[98:101], v[170:173], v[200:203], v[98:101]
	v_mfma_f32_16x16x32_bf16 v[90:93], v[178:181], v[200:203], v[90:93]
	v_mfma_f32_16x16x32_bf16 v[86:89], v[170:173], v[208:211], v[86:89]
	v_mfma_f32_16x16x32_bf16 v[78:81], v[178:181], v[208:211], v[78:81]
	v_mfma_f32_16x16x32_bf16 v[70:73], v[170:173], v[216:219], v[70:73]
	v_mfma_f32_16x16x32_bf16 v[66:69], v[178:181], v[216:219], v[66:69]
	v_mfma_f32_16x16x32_bf16 v[118:121], v[174:177], v[196:199], v[118:121]
	v_mfma_f32_16x16x32_bf16 v[110:113], v[188:191], v[196:199], v[110:113]
	v_mfma_f32_16x16x32_bf16 v[98:101], v[174:177], v[204:207], v[98:101]
	v_mfma_f32_16x16x32_bf16 v[90:93], v[188:191], v[204:207], v[90:93]
	v_mfma_f32_16x16x32_bf16 v[86:89], v[174:177], v[212:215], v[86:89]
	v_mfma_f32_16x16x32_bf16 v[78:81], v[188:191], v[212:215], v[78:81]
	v_mfma_f32_16x16x32_bf16 v[70:73], v[174:177], v[230:233], v[70:73]
	v_mfma_f32_16x16x32_bf16 v[66:69], v[188:191], v[230:233], v[66:69]
	s_setprio 0
	s_barrier
	s_add_i32 s47, s47, s27
	v_lshl_add_u64 v[146:147], s[18:19], 0, v[134:135]
	s_mov_b32 m0, s47
	ds_read_b128 v[192:195], v156 offset:16384
	ds_read_b128 v[196:199], v156 offset:17408
	ds_read_b128 v[200:203], v156 offset:18432
	ds_read_b128 v[204:207], v156 offset:19456
	ds_read_b128 v[208:211], v156 offset:20480
	ds_read_b128 v[212:215], v156 offset:21504
	ds_read_b128 v[216:219], v156 offset:22528
	ds_read_b128 v[230:233], v156 offset:23552
	global_load_lds_dwordx4 v[146:147], off
	s_add_i32 m0, s47, 0x2000
	s_add_u32 s48, s18, 0x40000
	v_lshl_add_u64 v[150:151], s[18:19], 0, v[130:131]
	s_addc_u32 s49, s19, 0
	s_add_i32 s47, s50, s27
	global_load_lds_dwordx4 v[150:151], off
	v_lshl_add_u64 v[182:183], s[48:49], 0, v[134:135]
	s_mov_b32 m0, s47
	v_lshl_add_u64 v[234:235], s[20:21], 0, v[132:133]
	global_load_lds_dwordx4 v[182:183], off
	v_lshl_add_u64 v[182:183], s[48:49], 0, v[130:131]
	s_add_i32 m0, s47, 0x2000
	s_nop 0
	global_load_lds_dwordx4 v[182:183], off
	v_lshl_add_u64 v[182:183], s[20:21], 0, v[136:137]
	s_mov_b32 m0, s28
	s_nop 0
	global_load_lds_dwordx4 v[182:183], off
	s_mov_b32 m0, s29
	s_nop 0
	global_load_lds_dwordx4 v[234:235], off
	s_waitcnt vmcnt(8)
	s_waitcnt lgkmcnt(0)
	s_barrier
; #define PG8_STAGE(bufoff, gbase, voff) do { _Pragma("unroll") for (int _i = 0; _i < 2; ++_i) \
;         __builtin_amdgcn_global_load_lds((const unsigned*)((const char*)(gbase) + (voff)[_i]), (PG8_LAS unsigned*)(lds + (bufoff) + ldsw + _i * 8192), 16, 0, 0); } while (0)
; #define PG8_LDA(dst, b, h) do { _Pragma("unroll") for (int m = 0; m < 4; ++m) _Pragma("unroll") for (int k = 0; k < 2; ++k) dst[m][k] = *(const PG8_LAS bf16x8*)(lds + PG8_SA(b, h) + aoff + m * 2048 + k * 1024); } while (0)
; #define PG8_LDB(dst, b, h) do { _Pragma("unroll") for (int n = 0; n < 2; ++n) _Pragma("unroll") for (int k = 0; k < 2; ++k) dst[n][k] = *(const PG8_LAS bf16x8*)(lds + PG8_SB(b, h) + boff + n * 2048 + k * 1024); } while (0)
; #define PG8_MMA(ai, bj, At, Bt) do { __builtin_amdgcn_s_setprio(1); _Pragma("unroll") for (int m = 0; m < 4; ++m) _Pragma("unroll") for (int n = 0; n < 2; ++n) _Pragma("unroll") for (int k = 0; k < 2; ++k) \
;         acc[ai][bj][m][n] = __builtin_amdgcn_mfma_f32_16x16x32_bf16(Bt[n][k], At[m][k], acc[ai][bj][m][n], 0, 0, 0); __builtin_amdgcn_s_setprio(0); } while (0)
; #define PG8_WAIT_V(n) asm volatile("s_waitcnt vmcnt(" #n ")" ::: "memory")
; #define PG8_WAIT_L(n) asm volatile("s_waitcnt lgkmcnt(" #n ")" ::: "memory")
; #define PG8_BAR __builtin_amdgcn_s_barrier()
; #define PG8_SCHED __builtin_amdgcn_sched_barrier(0)
; template <class Epi, class Sched, bool ALIGN_EPI = false, bool SP2 = false>
; __device__ __forceinline__ void gemm_phase(PG8_LAS unsigned char* lds, const Gemm g, const Sched& S, const Epi& E) {
;     ...
;             PG8_WAIT_V(8); PG8_WAIT_L(0); PG8_BAR; PG8_MMA(1, 0, At, B0); PG8_MMA(1, 1, At, B1); PG8_BAR; PG8_SCHED;
;             PG8_LDB(B0, 1, 0); PG8_LDB(B1, 1, 1); PG8_SCHED; PG8_LDA(At, 1, 0); PG8_STAGE(PG8_SA(0, 1), a2 + hstep, voffA);
;             PG8_WAIT_V(8); PG8_WAIT_L(0); PG8_BAR; PG8_MMA(0, 0, At, B0); PG8_MMA(0, 1, At, B1); PG8_BAR; PG8_SCHED;
	s_setprio 1
	v_mfma_f32_16x16x32_bf16 v[60:63], v[142:145], v[192:195], v[60:63]
	v_mfma_f32_16x16x32_bf16 v[56:59], v[162:165], v[192:195], v[56:59]
	v_mfma_f32_16x16x32_bf16 v[48:51], v[142:145], v[200:203], v[48:51]
	v_mfma_f32_16x16x32_bf16 v[40:43], v[162:165], v[200:203], v[40:43]
	v_mfma_f32_16x16x32_bf16 v[36:39], v[142:145], v[208:211], v[36:39]
	v_mfma_f32_16x16x32_bf16 v[28:31], v[162:165], v[208:211], v[28:31]
	v_mfma_f32_16x16x32_bf16 v[20:23], v[142:145], v[216:219], v[20:23]
	v_mfma_f32_16x16x32_bf16 v[12:15], v[162:165], v[216:219], v[12:15]
	v_mfma_f32_16x16x32_bf16 v[60:63], v[158:161], v[196:199], v[60:63]
	v_mfma_f32_16x16x32_bf16 v[56:59], v[166:169], v[196:199], v[56:59]
	v_mfma_f32_16x16x32_bf16 v[48:51], v[158:161], v[204:207], v[48:51]
	v_mfma_f32_16x16x32_bf16 v[40:43], v[166:169], v[204:207], v[40:43]
	v_mfma_f32_16x16x32_bf16 v[36:39], v[158:161], v[212:215], v[36:39]
	v_mfma_f32_16x16x32_bf16 v[28:31], v[166:169], v[212:215], v[28:31]
	v_mfma_f32_16x16x32_bf16 v[20:23], v[158:161], v[230:233], v[20:23]
	v_mfma_f32_16x16x32_bf16 v[12:15], v[166:169], v[230:233], v[12:15]
	v_mfma_f32_16x16x32_bf16 v[52:55], v[170:173], v[192:195], v[52:55]
	v_mfma_f32_16x16x32_bf16 v[44:47], v[178:181], v[192:195], v[44:47]
	v_mfma_f32_16x16x32_bf16 v[32:35], v[170:173], v[200:203], v[32:35]
	v_mfma_f32_16x16x32_bf16 v[24:27], v[178:181], v[200:203], v[24:27]
	v_mfma_f32_16x16x32_bf16 v[16:19], v[170:173], v[208:211], v[16:19]
	v_mfma_f32_16x16x32_bf16 v[8:11], v[178:181], v[208:211], v[8:11]
	v_mfma_f32_16x16x32_bf16 v[4:7], v[170:173], v[216:219], v[4:7]
	v_mfma_f32_16x16x32_bf16 v[0:3], v[178:181], v[216:219], v[0:3]
	v_mfma_f32_16x16x32_bf16 v[52:55], v[174:177], v[196:199], v[52:55]
	v_mfma_f32_16x16x32_bf16 v[44:47], v[188:191], v[196:199], v[44:47]
	v_mfma_f32_16x16x32_bf16 v[32:35], v[174:177], v[204:207], v[32:35]
	v_mfma_f32_16x16x32_bf16 v[24:27], v[188:191], v[204:207], v[24:27]
	v_mfma_f32_16x16x32_bf16 v[16:19], v[174:177], v[212:215], v[16:19]
	v_mfma_f32_16x16x32_bf16 v[8:11], v[188:191], v[212:215], v[8:11]
	v_mfma_f32_16x16x32_bf16 v[4:7], v[174:177], v[230:233], v[4:7]
	v_mfma_f32_16x16x32_bf16 v[0:3], v[188:191], v[230:233], v[0:3]
	s_setprio 0
	s_barrier
	s_add_i32 s47, 0, 0x18000
	v_add_u32_e32 v64, s47, v152
	s_add_i32 s48, 0, 0x1c000
	ds_read_b128 v[142:145], v64
	ds_read_b128 v[158:161], v64 offset:1024
	ds_read_b128 v[162:165], v64 offset:2048
	ds_read_b128 v[166:169], v64 offset:3072
	v_add_u32_e32 v64, s48, v152
	ds_read_b128 v[170:173], v64
	ds_read_b128 v[174:177], v64 offset:1024
	ds_read_b128 v[178:181], v64 offset:2048
	ds_read_b128 v[188:191], v64 offset:3072
	s_add_u32 s20, s20, 0x40000
	s_addc_u32 s21, s21, 0
	s_mov_b32 m0, s33
	v_lshl_add_u64 v[236:237], s[20:21], 0, v[136:137]
	ds_read_b128 v[192:195], v156 offset:32768
	ds_read_b128 v[196:199], v156 offset:33792
	ds_read_b128 v[200:203], v156 offset:34816
	ds_read_b128 v[204:207], v156 offset:35840
	ds_read_b128 v[208:211], v156 offset:36864
	ds_read_b128 v[212:215], v156 offset:37888
	ds_read_b128 v[216:219], v156 offset:38912
	ds_read_b128 v[230:233], v156 offset:39936
	global_load_lds_dwordx4 v[236:237], off
	v_lshl_add_u64 v[236:237], s[20:21], 0, v[132:133]
	s_mov_b32 m0, s34
	s_nop 0
	global_load_lds_dwordx4 v[236:237], off
	s_waitcnt vmcnt(8)
	s_waitcnt lgkmcnt(0)
	s_barrier
	s_setprio 1
	v_mfma_f32_16x16x32_bf16 v[126:129], v[142:145], v[192:195], v[126:129]
	v_mfma_f32_16x16x32_bf16 v[122:125], v[162:165], v[192:195], v[122:125]
	v_mfma_f32_16x16x32_bf16 v[114:117], v[142:145], v[200:203], v[114:117]
	v_mfma_f32_16x16x32_bf16 v[106:109], v[162:165], v[200:203], v[106:109]
	v_mfma_f32_16x16x32_bf16 v[102:105], v[142:145], v[208:211], v[102:105]
	v_mfma_f32_16x16x32_bf16 v[94:97], v[162:165], v[208:211], v[94:97]
	v_mfma_f32_16x16x32_bf16 v[82:85], v[142:145], v[216:219], v[82:85]
	v_mfma_f32_16x16x32_bf16 v[74:77], v[162:165], v[216:219], v[74:77]
	v_mfma_f32_16x16x32_bf16 v[126:129], v[158:161], v[196:199], v[126:129]
	v_mfma_f32_16x16x32_bf16 v[122:125], v[166:169], v[196:199], v[122:125]
	v_mfma_f32_16x16x32_bf16 v[114:117], v[158:161], v[204:207], v[114:117]
	v_mfma_f32_16x16x32_bf16 v[106:109], v[166:169], v[204:207], v[106:109]
	v_mfma_f32_16x16x32_bf16 v[102:105], v[158:161], v[212:215], v[102:105]
	v_mfma_f32_16x16x32_bf16 v[94:97], v[166:169], v[212:215], v[94:97]
	v_mfma_f32_16x16x32_bf16 v[82:85], v[158:161], v[230:233], v[82:85]
	v_mfma_f32_16x16x32_bf16 v[74:77], v[166:169], v[230:233], v[74:77]
	v_mfma_f32_16x16x32_bf16 v[118:121], v[170:173], v[192:195], v[118:121]
	v_mfma_f32_16x16x32_bf16 v[110:113], v[178:181], v[192:195], v[110:113]
	v_mfma_f32_16x16x32_bf16 v[98:101], v[170:173], v[200:203], v[98:101]
	v_mfma_f32_16x16x32_bf16 v[90:93], v[178:181], v[200:203], v[90:93]
	v_mfma_f32_16x16x32_bf16 v[86:89], v[170:173], v[208:211], v[86:89]
	v_mfma_f32_16x16x32_bf16 v[78:81], v[178:181], v[208:211], v[78:81]
	v_mfma_f32_16x16x32_bf16 v[70:73], v[170:173], v[216:219], v[70:73]
	v_mfma_f32_16x16x32_bf16 v[66:69], v[178:181], v[216:219], v[66:69]
	v_mfma_f32_16x16x32_bf16 v[118:121], v[174:177], v[196:199], v[118:121]
	v_mfma_f32_16x16x32_bf16 v[110:113], v[188:191], v[196:199], v[110:113]
	v_mfma_f32_16x16x32_bf16 v[98:101], v[174:177], v[204:207], v[98:101]
	v_mfma_f32_16x16x32_bf16 v[90:93], v[188:191], v[204:207], v[90:93]
	v_mfma_f32_16x16x32_bf16 v[86:89], v[174:177], v[212:215], v[86:89]
	v_mfma_f32_16x16x32_bf16 v[78:81], v[188:191], v[212:215], v[78:81]
	v_mfma_f32_16x16x32_bf16 v[70:73], v[174:177], v[230:233], v[70:73]
	v_mfma_f32_16x16x32_bf16 v[66:69], v[188:191], v[230:233], v[66:69]
	s_setprio 0
	s_barrier
; #define PG8_STAGE(bufoff, gbase, voff) do { _Pragma("unroll") for (int _i = 0; _i < 2; ++_i) \
;         __builtin_amdgcn_global_load_lds((const unsigned*)((const char*)(gbase) + (voff)[_i]), (PG8_LAS unsigned*)(lds + (bufoff) + ldsw + _i * 8192), 16, 0, 0); } while (0)
; #define PG8_LDA(dst, b, h) do { _Pragma("unroll") for (int m = 0; m < 4; ++m) _Pragma("unroll") for (int k = 0; k < 2; ++k) dst[m][k] = *(const PG8_LAS bf16x8*)(lds + PG8_SA(b, h) + aoff + m * 2048 + k * 1024); } while (0)
; #define PG8_MMA(ai, bj, At, Bt) do { __builtin_amdgcn_s_setprio(1); _Pragma("unroll") for (int m = 0; m < 4; ++m) _Pragma("unroll") for (int n = 0; n < 2; ++n) _Pragma("unroll") for (int k = 0; k < 2; ++k) \
;         acc[ai][bj][m][n] = __builtin_amdgcn_mfma_f32_16x16x32_bf16(Bt[n][k], At[m][k], acc[ai][bj][m][n], 0, 0, 0); __builtin_amdgcn_s_setprio(0); } while (0)
; #define PG8_WAIT_V(n) asm volatile("s_waitcnt vmcnt(" #n ")" ::: "memory")
; #define PG8_WAIT_L(n) asm volatile("s_waitcnt lgkmcnt(" #n ")" ::: "memory")
; #define PG8_BAR __builtin_amdgcn_s_barrier()
; #define PG8_SCHED __builtin_amdgcn_sched_barrier(0)
; template <class Epi, class Sched, bool ALIGN_EPI = false, bool SP2 = false>
; __device__ __forceinline__ void gemm_phase(PG8_LAS unsigned char* lds, const Gemm g, const Sched& S, const Epi& E) {
;     ...
;             PG8_LDA(At, 1, 1); PG8_STAGE(PG8_SB(1, 0), b3, voffB); PG8_STAGE(PG8_SB(1, 1), b3 + hstep, voffB); PG8_STAGE(PG8_SA(1, 0), a3, voffA);
;             PG8_WAIT_V(8); PG8_WAIT_L(0); PG8_BAR; PG8_MMA(1, 0, At, B0); PG8_MMA(1, 1, At, B1); PG8_BAR; PG8_SCHED;
	s_add_i32 s20, s47, s27
	v_lshl_add_u64 v[146:147], v[146:147], 0, s[52:53]
	s_mov_b32 m0, s20
	ds_read_b128 v[192:195], v156 offset:49152
	ds_read_b128 v[196:199], v156 offset:50176
	ds_read_b128 v[200:203], v156 offset:51200
	ds_read_b128 v[204:207], v156 offset:52224
	ds_read_b128 v[208:211], v156 offset:53248
	ds_read_b128 v[212:215], v156 offset:54272
	ds_read_b128 v[216:219], v156 offset:55296
	ds_read_b128 v[230:233], v156 offset:56320
	global_load_lds_dwordx4 v[146:147], off
	s_add_i32 m0, s20, 0x2000
	s_add_u32 s18, s18, 0x40080
	v_lshl_add_u64 v[146:147], v[150:151], 0, s[52:53]
	s_addc_u32 s19, s19, 0
	s_add_i32 s20, s48, s27
	global_load_lds_dwordx4 v[146:147], off
	v_lshl_add_u64 v[146:147], s[18:19], 0, v[134:135]
	s_mov_b32 m0, s20
	s_nop 0
	global_load_lds_dwordx4 v[146:147], off
	v_lshl_add_u64 v[146:147], s[18:19], 0, v[130:131]
	s_add_i32 m0, s20, 0x2000
	s_nop 0
	global_load_lds_dwordx4 v[146:147], off
	v_lshl_add_u64 v[146:147], v[182:183], 0, s[52:53]
	s_mov_b32 m0, s35
	s_nop 0
	global_load_lds_dwordx4 v[146:147], off
	v_lshl_add_u64 v[146:147], v[234:235], 0, s[52:53]
	s_mov_b32 m0, s36
	s_nop 0
	global_load_lds_dwordx4 v[146:147], off
	s_waitcnt vmcnt(8)
	s_waitcnt lgkmcnt(0)
	s_barrier
	s_setprio 1
	v_mfma_f32_16x16x32_bf16 v[60:63], v[142:145], v[192:195], v[60:63]
	v_mfma_f32_16x16x32_bf16 v[56:59], v[162:165], v[192:195], v[56:59]
	v_mfma_f32_16x16x32_bf16 v[48:51], v[142:145], v[200:203], v[48:51]
	v_mfma_f32_16x16x32_bf16 v[40:43], v[162:165], v[200:203], v[40:43]
	v_mfma_f32_16x16x32_bf16 v[36:39], v[142:145], v[208:211], v[36:39]
	v_mfma_f32_16x16x32_bf16 v[28:31], v[162:165], v[208:211], v[28:31]
	v_mfma_f32_16x16x32_bf16 v[20:23], v[142:145], v[216:219], v[20:23]
	v_mfma_f32_16x16x32_bf16 v[12:15], v[162:165], v[216:219], v[12:15]
	v_mfma_f32_16x16x32_bf16 v[60:63], v[158:161], v[196:199], v[60:63]
	v_mfma_f32_16x16x32_bf16 v[56:59], v[166:169], v[196:199], v[56:59]
	v_mfma_f32_16x16x32_bf16 v[48:51], v[158:161], v[204:207], v[48:51]
	v_mfma_f32_16x16x32_bf16 v[40:43], v[166:169], v[204:207], v[40:43]
	v_mfma_f32_16x16x32_bf16 v[36:39], v[158:161], v[212:215], v[36:39]
	v_mfma_f32_16x16x32_bf16 v[28:31], v[166:169], v[212:215], v[28:31]
	v_mfma_f32_16x16x32_bf16 v[20:23], v[158:161], v[230:233], v[20:23]
	v_mfma_f32_16x16x32_bf16 v[12:15], v[166:169], v[230:233], v[12:15]
	v_mfma_f32_16x16x32_bf16 v[52:55], v[170:173], v[192:195], v[52:55]
	v_mfma_f32_16x16x32_bf16 v[44:47], v[178:181], v[192:195], v[44:47]
	v_mfma_f32_16x16x32_bf16 v[32:35], v[170:173], v[200:203], v[32:35]
	v_mfma_f32_16x16x32_bf16 v[24:27], v[178:181], v[200:203], v[24:27]
	v_mfma_f32_16x16x32_bf16 v[16:19], v[170:173], v[208:211], v[16:19]
	v_mfma_f32_16x16x32_bf16 v[8:11], v[178:181], v[208:211], v[8:11]
	v_mfma_f32_16x16x32_bf16 v[4:7], v[170:173], v[216:219], v[4:7]
	v_mfma_f32_16x16x32_bf16 v[0:3], v[178:181], v[216:219], v[0:3]
	v_mfma_f32_16x16x32_bf16 v[52:55], v[174:177], v[196:199], v[52:55]
	v_mfma_f32_16x16x32_bf16 v[44:47], v[188:191], v[196:199], v[44:47]
	v_mfma_f32_16x16x32_bf16 v[32:35], v[174:177], v[204:207], v[32:35]
	v_mfma_f32_16x16x32_bf16 v[24:27], v[188:191], v[204:207], v[24:27]
	v_mfma_f32_16x16x32_bf16 v[16:19], v[174:177], v[212:215], v[16:19]
	v_mfma_f32_16x16x32_bf16 v[8:11], v[188:191], v[212:215], v[8:11]
	v_mfma_f32_16x16x32_bf16 v[4:7], v[174:177], v[230:233], v[4:7]
	v_mfma_f32_16x16x32_bf16 v[0:3], v[188:191], v[230:233], v[0:3]
	s_setprio 0
	s_barrier
	s_add_i32 s46, s46, 2
	s_add_u32 s16, s16, 0x100
	s_addc_u32 s17, s17, 0
	s_add_u32 s44, s44, 0x100
	s_addc_u32 s45, s45, 0
	s_cmp_gt_u32 s46, 13
	s_cbranch_scc0 .LBB0_252
	s_and_b64 vcc, exec, s[4:5]
	s_cbranch_vccz .LBB0_255
	s_barrier

; #define PG8_STAGE(bufoff, gbase, voff) do { _Pragma("unroll") for (int _i = 0; _i < 2; ++_i) \
;         __builtin_amdgcn_global_load_lds((const unsigned*)((const char*)(gbase) + (voff)[_i]), (PG8_LAS unsigned*)(lds + (bufoff) + ldsw + _i * 8192), 16, 0, 0); } while (0)
; #define PG8_LDA(dst, b, h) do { _Pragma("unroll") for (int m = 0; m < 4; ++m) _Pragma("unroll") for (int k = 0; k < 2; ++k) dst[m][k] = *(const PG8_LAS bf16x8*)(lds + PG8_SA(b, h) + aoff + m * 2048 + k * 1024); } while (0)
; #define PG8_LDB(dst, b, h) do { _Pragma("unroll") for (int n = 0; n < 2; ++n) _Pragma("unroll") for (int k = 0; k < 2; ++k) dst[n][k] = *(const PG8_LAS bf16x8*)(lds + PG8_SB(b, h) + boff + n * 2048 + k * 1024); } while (0)
; #define PG8_MMA(ai, bj, At, Bt) do { __builtin_amdgcn_s_setprio(1); _Pragma("unroll") for (int m = 0; m < 4; ++m) _Pragma("unroll") for (int n = 0; n < 2; ++n) _Pragma("unroll") for (int k = 0; k < 2; ++k) \
;         acc[ai][bj][m][n] = __builtin_amdgcn_mfma_f32_16x16x32_bf16(Bt[n][k], At[m][k], acc[ai][bj][m][n], 0, 0, 0); __builtin_amdgcn_s_setprio(0); } while (0)
; #define PG8_WAIT_V(n) asm volatile("s_waitcnt vmcnt(" #n ")" ::: "memory")
; #define PG8_WAIT_L(n) asm volatile("s_waitcnt lgkmcnt(" #n ")" ::: "memory")
; template <class Epi, class Sched, bool ALIGN_EPI = false, bool SP2 = false>
; __device__ __forceinline__ void gemm_phase(PG8_LAS unsigned char* lds, const Gemm g, const Sched& S, const Epi& E) {
;     ...
;             const bool last = (t == nt - 2);
;             const char* a1 = cA + (size_t)(t + 1) * kstep;
;             const char* a2 = last ? nA : cA + (size_t)(t + 2) * kstep; const char* b2 = last ? nB : cB + (size_t)(t + 2) * kstep;
;             const char* a3 = a2 + kstep; const char* b3 = b2 + kstep;
;             if (last && has_next) S.a_ready(nxt);
;             if constexpr (SP2) {
;             PG8_LDB(B0, 0, 0); PG8_LDB(B1, 0, 1); PG8_SCHED; PG8_LDA(At, 0, 0); PG8_STAGE(PG8_SA(1, 1), a1 + hstep, voffA);
;             PG8_WAIT_V(8); PG8_WAIT_L(0); PG8_BAR; PG8_MMA(0, 0, At, B0); PG8_MMA(0, 1, At, B1); PG8_BAR; PG8_SCHED;
;             PG8_LDA(At, 0, 1); PG8_STAGE(PG8_SB(0, 0), b2, voffB); PG8_STAGE(PG8_SB(0, 1), b2 + hstep, voffB); PG8_STAGE(PG8_SA(0, 0), a2, voffA);
;             PG8_WAIT_V(8); PG8_WAIT_L(0); PG8_BAR; PG8_MMA(1, 0, At, B0); PG8_MMA(1, 1, At, B1); PG8_BAR; PG8_SCHED;
.LBB0_473:
	s_add_u32 s8, s6, 0xfffc0080
	s_addc_u32 s9, s7, -1
	s_add_i32 s33, 0, 0x10000
	s_cmp_eq_u32 s29, 12
	s_cselect_b32 s11, s5, s9
	s_cselect_b32 s10, s24, s8
	v_add_u32_e32 v64, s33, v161
	s_cselect_b32 s9, s25, s28
	s_cselect_b32 s8, s26, s27
	s_add_i32 s36, 0, 0x14000
	ds_read_b128 v[130:133], v64
	ds_read_b128 v[134:137], v64 offset:1024
	ds_read_b128 v[138:141], v64 offset:2048
	ds_read_b128 v[142:145], v64 offset:3072
	v_add_u32_e32 v64, s36, v161
	ds_read_b128 v[166:169], v64
	ds_read_b128 v[170:173], v64 offset:1024
	ds_read_b128 v[174:177], v64 offset:2048
	ds_read_b128 v[178:181], v64 offset:3072
	v_lshl_add_u64 v[158:159], s[6:7], 0, v[154:155]
	s_add_i32 m0, s16, 0xc000
	ds_read_b128 v[188:191], v164
	ds_read_b128 v[192:195], v164 offset:1024
	ds_read_b128 v[196:199], v164 offset:2048
	ds_read_b128 v[200:203], v164 offset:3072
	ds_read_b128 v[204:207], v164 offset:4096
	ds_read_b128 v[208:211], v164 offset:5120
	ds_read_b128 v[212:215], v164 offset:6144
	ds_read_b128 v[216:219], v164 offset:7168
	global_load_lds_dwordx4 v[158:159], off
	v_lshl_add_u64 v[158:159], s[6:7], 0, v[156:157]
	s_add_i32 m0, s16, 0xe000
	s_nop 0
	global_load_lds_dwordx4 v[158:159], off
	s_waitcnt vmcnt(8)
	s_waitcnt lgkmcnt(0)
	s_barrier
	s_setprio 1
	v_mfma_f32_16x16x32_bf16 v[126:129], v[130:133], v[188:191], v[126:129]
	v_mfma_f32_16x16x32_bf16 v[122:125], v[138:141], v[188:191], v[122:125]
	v_mfma_f32_16x16x32_bf16 v[110:113], v[130:133], v[196:199], v[110:113]
	v_mfma_f32_16x16x32_bf16 v[106:109], v[138:141], v[196:199], v[106:109]
	v_mfma_f32_16x16x32_bf16 v[94:97], v[130:133], v[204:207], v[94:97]
	v_mfma_f32_16x16x32_bf16 v[90:93], v[138:141], v[204:207], v[90:93]
	v_mfma_f32_16x16x32_bf16 v[78:81], v[130:133], v[212:215], v[78:81]
	v_mfma_f32_16x16x32_bf16 v[74:77], v[138:141], v[212:215], v[74:77]
	v_mfma_f32_16x16x32_bf16 v[126:129], v[134:137], v[192:195], v[126:129]
	v_mfma_f32_16x16x32_bf16 v[122:125], v[142:145], v[192:195], v[122:125]
	v_mfma_f32_16x16x32_bf16 v[110:113], v[134:137], v[200:203], v[110:113]
	v_mfma_f32_16x16x32_bf16 v[106:109], v[142:145], v[200:203], v[106:109]
	v_mfma_f32_16x16x32_bf16 v[94:97], v[134:137], v[208:211], v[94:97]
	v_mfma_f32_16x16x32_bf16 v[90:93], v[142:145], v[208:211], v[90:93]
	v_mfma_f32_16x16x32_bf16 v[78:81], v[134:137], v[216:219], v[78:81]
	v_mfma_f32_16x16x32_bf16 v[74:77], v[142:145], v[216:219], v[74:77]
	v_mfma_f32_16x16x32_bf16 v[118:121], v[166:169], v[188:191], v[118:121]
	v_mfma_f32_16x16x32_bf16 v[114:117], v[174:177], v[188:191], v[114:117]
	v_mfma_f32_16x16x32_bf16 v[102:105], v[166:169], v[196:199], v[102:105]
	v_mfma_f32_16x16x32_bf16 v[98:101], v[174:177], v[196:199], v[98:101]
	v_mfma_f32_16x16x32_bf16 v[86:89], v[166:169], v[204:207], v[86:89]
	v_mfma_f32_16x16x32_bf16 v[82:85], v[174:177], v[204:207], v[82:85]
	v_mfma_f32_16x16x32_bf16 v[70:73], v[166:169], v[212:215], v[70:73]
	v_mfma_f32_16x16x32_bf16 v[66:69], v[174:177], v[212:215], v[66:69]
	v_mfma_f32_16x16x32_bf16 v[118:121], v[170:173], v[192:195], v[118:121]
	v_mfma_f32_16x16x32_bf16 v[114:117], v[178:181], v[192:195], v[114:117]
	v_mfma_f32_16x16x32_bf16 v[102:105], v[170:173], v[200:203], v[102:105]
	v_mfma_f32_16x16x32_bf16 v[98:101], v[178:181], v[200:203], v[98:101]
	v_mfma_f32_16x16x32_bf16 v[86:89], v[170:173], v[208:211], v[86:89]
	v_mfma_f32_16x16x32_bf16 v[82:85], v[178:181], v[208:211], v[82:85]
	v_mfma_f32_16x16x32_bf16 v[70:73], v[170:173], v[216:219], v[70:73]
	v_mfma_f32_16x16x32_bf16 v[66:69], v[178:181], v[216:219], v[66:69]
	s_setprio 0
	s_barrier
	s_add_i32 s33, s33, s15
	v_lshl_add_u64 v[158:159], s[8:9], 0, v[148:149]
	s_mov_b32 m0, s33
	ds_read_b128 v[188:191], v164 offset:16384
	ds_read_b128 v[192:195], v164 offset:17408
	ds_read_b128 v[196:199], v164 offset:18432
	ds_read_b128 v[200:203], v164 offset:19456
	ds_read_b128 v[204:207], v164 offset:20480
	ds_read_b128 v[208:211], v164 offset:21504
	ds_read_b128 v[212:215], v164 offset:22528
	ds_read_b128 v[216:219], v164 offset:23552
	global_load_lds_dwordx4 v[158:159], off
	s_add_i32 m0, s33, 0x2000
	s_add_u32 s34, s8, 0x40000
	v_lshl_add_u64 v[182:183], s[8:9], 0, v[152:153]
	s_addc_u32 s35, s9, 0
	s_add_i32 s33, s36, s15
	global_load_lds_dwordx4 v[182:183], off
	v_lshl_add_u64 v[230:231], s[34:35], 0, v[148:149]
	s_mov_b32 m0, s33
	v_lshl_add_u64 v[232:233], s[10:11], 0, v[150:151]
	global_load_lds_dwordx4 v[230:231], off
	v_lshl_add_u64 v[230:231], s[34:35], 0, v[152:153]
	s_add_i32 m0, s33, 0x2000
	s_nop 0
	global_load_lds_dwordx4 v[230:231], off
	v_lshl_add_u64 v[230:231], s[10:11], 0, v[146:147]
	s_mov_b32 m0, s16
	s_nop 0
	global_load_lds_dwordx4 v[230:231], off
	s_mov_b32 m0, s17
	s_nop 0
	global_load_lds_dwordx4 v[232:233], off
	s_waitcnt vmcnt(8)
	s_waitcnt lgkmcnt(0)
	s_barrier
; #define PG8_STAGE(bufoff, gbase, voff) do { _Pragma("unroll") for (int _i = 0; _i < 2; ++_i) \
;         __builtin_amdgcn_global_load_lds((const unsigned*)((const char*)(gbase) + (voff)[_i]), (PG8_LAS unsigned*)(lds + (bufoff) + ldsw + _i * 8192), 16, 0, 0); } while (0)
; #define PG8_LDA(dst, b, h) do { _Pragma("unroll") for (int m = 0; m < 4; ++m) _Pragma("unroll") for (int k = 0; k < 2; ++k) dst[m][k] = *(const PG8_LAS bf16x8*)(lds + PG8_SA(b, h) + aoff + m * 2048 + k * 1024); } while (0)
; #define PG8_LDB(dst, b, h) do { _Pragma("unroll") for (int n = 0; n < 2; ++n) _Pragma("unroll") for (int k = 0; k < 2; ++k) dst[n][k] = *(const PG8_LAS bf16x8*)(lds + PG8_SB(b, h) + boff + n * 2048 + k * 1024); } while (0)
; #define PG8_MMA(ai, bj, At, Bt) do { __builtin_amdgcn_s_setprio(1); _Pragma("unroll") for (int m = 0; m < 4; ++m) _Pragma("unroll") for (int n = 0; n < 2; ++n) _Pragma("unroll") for (int k = 0; k < 2; ++k) \
;         acc[ai][bj][m][n] = __builtin_amdgcn_mfma_f32_16x16x32_bf16(Bt[n][k], At[m][k], acc[ai][bj][m][n], 0, 0, 0); __builtin_amdgcn_s_setprio(0); } while (0)
; #define PG8_WAIT_V(n) asm volatile("s_waitcnt vmcnt(" #n ")" ::: "memory")
; #define PG8_WAIT_L(n) asm volatile("s_waitcnt lgkmcnt(" #n ")" ::: "memory")
; #define PG8_BAR __builtin_amdgcn_s_barrier()
; #define PG8_SCHED __builtin_amdgcn_sched_barrier(0)
; template <class Epi, class Sched, bool ALIGN_EPI = false, bool SP2 = false>
; __device__ __forceinline__ void gemm_phase(PG8_LAS unsigned char* lds, const Gemm g, const Sched& S, const Epi& E) {
;     ...
;             PG8_WAIT_V(8); PG8_WAIT_L(0); PG8_BAR; PG8_MMA(1, 0, At, B0); PG8_MMA(1, 1, At, B1); PG8_BAR; PG8_SCHED;
;             PG8_LDB(B0, 1, 0); PG8_LDB(B1, 1, 1); PG8_SCHED; PG8_LDA(At, 1, 0); PG8_STAGE(PG8_SA(0, 1), a2 + hstep, voffA);
;             PG8_WAIT_V(8); PG8_WAIT_L(0); PG8_BAR; PG8_MMA(0, 0, At, B0); PG8_MMA(0, 1, At, B1); PG8_BAR; PG8_SCHED;
	s_setprio 1
	v_mfma_f32_16x16x32_bf16 v[60:63], v[130:133], v[188:191], v[60:63]
	v_mfma_f32_16x16x32_bf16 v[56:59], v[138:141], v[188:191], v[56:59]
	v_mfma_f32_16x16x32_bf16 v[44:47], v[130:133], v[196:199], v[44:47]
	v_mfma_f32_16x16x32_bf16 v[40:43], v[138:141], v[196:199], v[40:43]
	v_mfma_f32_16x16x32_bf16 v[28:31], v[130:133], v[204:207], v[28:31]
	v_mfma_f32_16x16x32_bf16 v[24:27], v[138:141], v[204:207], v[24:27]
	v_mfma_f32_16x16x32_bf16 v[12:15], v[130:133], v[212:215], v[12:15]
	v_mfma_f32_16x16x32_bf16 v[8:11], v[138:141], v[212:215], v[8:11]
	v_mfma_f32_16x16x32_bf16 v[60:63], v[134:137], v[192:195], v[60:63]
	v_mfma_f32_16x16x32_bf16 v[56:59], v[142:145], v[192:195], v[56:59]
	v_mfma_f32_16x16x32_bf16 v[44:47], v[134:137], v[200:203], v[44:47]
	v_mfma_f32_16x16x32_bf16 v[40:43], v[142:145], v[200:203], v[40:43]
	v_mfma_f32_16x16x32_bf16 v[28:31], v[134:137], v[208:211], v[28:31]
	v_mfma_f32_16x16x32_bf16 v[24:27], v[142:145], v[208:211], v[24:27]
	v_mfma_f32_16x16x32_bf16 v[12:15], v[134:137], v[216:219], v[12:15]
	v_mfma_f32_16x16x32_bf16 v[8:11], v[142:145], v[216:219], v[8:11]
	v_mfma_f32_16x16x32_bf16 v[52:55], v[166:169], v[188:191], v[52:55]
	v_mfma_f32_16x16x32_bf16 v[48:51], v[174:177], v[188:191], v[48:51]
	v_mfma_f32_16x16x32_bf16 v[36:39], v[166:169], v[196:199], v[36:39]
	v_mfma_f32_16x16x32_bf16 v[32:35], v[174:177], v[196:199], v[32:35]
	v_mfma_f32_16x16x32_bf16 v[20:23], v[166:169], v[204:207], v[20:23]
	v_mfma_f32_16x16x32_bf16 v[16:19], v[174:177], v[204:207], v[16:19]
	v_mfma_f32_16x16x32_bf16 v[4:7], v[166:169], v[212:215], v[4:7]
	v_mfma_f32_16x16x32_bf16 v[0:3], v[174:177], v[212:215], v[0:3]
	v_mfma_f32_16x16x32_bf16 v[52:55], v[170:173], v[192:195], v[52:55]
	v_mfma_f32_16x16x32_bf16 v[48:51], v[178:181], v[192:195], v[48:51]
	v_mfma_f32_16x16x32_bf16 v[36:39], v[170:173], v[200:203], v[36:39]
	v_mfma_f32_16x16x32_bf16 v[32:35], v[178:181], v[200:203], v[32:35]
	v_mfma_f32_16x16x32_bf16 v[20:23], v[170:173], v[208:211], v[20:23]
	v_mfma_f32_16x16x32_bf16 v[16:19], v[178:181], v[208:211], v[16:19]
	v_mfma_f32_16x16x32_bf16 v[4:7], v[170:173], v[216:219], v[4:7]
	v_mfma_f32_16x16x32_bf16 v[0:3], v[178:181], v[216:219], v[0:3]
	s_setprio 0
	s_barrier
	s_add_i32 s33, 0, 0x18000
	v_add_u32_e32 v64, s33, v161
	s_add_i32 s34, 0, 0x1c000
	ds_read_b128 v[130:133], v64
	ds_read_b128 v[134:137], v64 offset:1024
	ds_read_b128 v[138:141], v64 offset:2048
	ds_read_b128 v[142:145], v64 offset:3072
	v_add_u32_e32 v64, s34, v161
	ds_read_b128 v[166:169], v64
	ds_read_b128 v[170:173], v64 offset:1024
	ds_read_b128 v[174:177], v64 offset:2048
	ds_read_b128 v[178:181], v64 offset:3072
	s_add_u32 s10, s10, 0x40000
	s_addc_u32 s11, s11, 0
	s_mov_b32 m0, s18
	v_lshl_add_u64 v[234:235], s[10:11], 0, v[146:147]
	ds_read_b128 v[188:191], v164 offset:32768
	ds_read_b128 v[192:195], v164 offset:33792
	ds_read_b128 v[196:199], v164 offset:34816
	ds_read_b128 v[200:203], v164 offset:35840
	ds_read_b128 v[204:207], v164 offset:36864
	ds_read_b128 v[208:211], v164 offset:37888
	ds_read_b128 v[212:215], v164 offset:38912
	ds_read_b128 v[216:219], v164 offset:39936
	global_load_lds_dwordx4 v[234:235], off
	v_lshl_add_u64 v[234:235], s[10:11], 0, v[150:151]
	s_mov_b32 m0, s19
	s_nop 0
	global_load_lds_dwordx4 v[234:235], off
	s_waitcnt vmcnt(8)
	s_waitcnt lgkmcnt(0)
	s_barrier
	s_setprio 1
	v_mfma_f32_16x16x32_bf16 v[126:129], v[130:133], v[188:191], v[126:129]
	v_mfma_f32_16x16x32_bf16 v[122:125], v[138:141], v[188:191], v[122:125]
	v_mfma_f32_16x16x32_bf16 v[110:113], v[130:133], v[196:199], v[110:113]
	v_mfma_f32_16x16x32_bf16 v[106:109], v[138:141], v[196:199], v[106:109]
	v_mfma_f32_16x16x32_bf16 v[94:97], v[130:133], v[204:207], v[94:97]
	v_mfma_f32_16x16x32_bf16 v[90:93], v[138:141], v[204:207], v[90:93]
	v_mfma_f32_16x16x32_bf16 v[78:81], v[130:133], v[212:215], v[78:81]
	v_mfma_f32_16x16x32_bf16 v[74:77], v[138:141], v[212:215], v[74:77]
	v_mfma_f32_16x16x32_bf16 v[126:129], v[134:137], v[192:195], v[126:129]
	v_mfma_f32_16x16x32_bf16 v[122:125], v[142:145], v[192:195], v[122:125]
	v_mfma_f32_16x16x32_bf16 v[110:113], v[134:137], v[200:203], v[110:113]
	v_mfma_f32_16x16x32_bf16 v[106:109], v[142:145], v[200:203], v[106:109]
	v_mfma_f32_16x16x32_bf16 v[94:97], v[134:137], v[208:211], v[94:97]
	v_mfma_f32_16x16x32_bf16 v[90:93], v[142:145], v[208:211], v[90:93]
	v_mfma_f32_16x16x32_bf16 v[78:81], v[134:137], v[216:219], v[78:81]
	v_mfma_f32_16x16x32_bf16 v[74:77], v[142:145], v[216:219], v[74:77]
	v_mfma_f32_16x16x32_bf16 v[118:121], v[166:169], v[188:191], v[118:121]
	v_mfma_f32_16x16x32_bf16 v[114:117], v[174:177], v[188:191], v[114:117]
	v_mfma_f32_16x16x32_bf16 v[102:105], v[166:169], v[196:199], v[102:105]
	v_mfma_f32_16x16x32_bf16 v[98:101], v[174:177], v[196:199], v[98:101]
	v_mfma_f32_16x16x32_bf16 v[86:89], v[166:169], v[204:207], v[86:89]
	v_mfma_f32_16x16x32_bf16 v[82:85], v[174:177], v[204:207], v[82:85]
	v_mfma_f32_16x16x32_bf16 v[70:73], v[166:169], v[212:215], v[70:73]
	v_mfma_f32_16x16x32_bf16 v[66:69], v[174:177], v[212:215], v[66:69]
	v_mfma_f32_16x16x32_bf16 v[118:121], v[170:173], v[192:195], v[118:121]
	v_mfma_f32_16x16x32_bf16 v[114:117], v[178:181], v[192:195], v[114:117]
	v_mfma_f32_16x16x32_bf16 v[102:105], v[170:173], v[200:203], v[102:105]
	v_mfma_f32_16x16x32_bf16 v[98:101], v[178:181], v[200:203], v[98:101]
	v_mfma_f32_16x16x32_bf16 v[86:89], v[170:173], v[208:211], v[86:89]
	v_mfma_f32_16x16x32_bf16 v[82:85], v[178:181], v[208:211], v[82:85]
	v_mfma_f32_16x16x32_bf16 v[70:73], v[170:173], v[216:219], v[70:73]
	v_mfma_f32_16x16x32_bf16 v[66:69], v[178:181], v[216:219], v[66:69]
	s_setprio 0
	s_barrier
; #define PG8_STAGE(bufoff, gbase, voff) do { _Pragma("unroll") for (int _i = 0; _i < 2; ++_i) \
;         __builtin_amdgcn_global_load_lds((const unsigned*)((const char*)(gbase) + (voff)[_i]), (PG8_LAS unsigned*)(lds + (bufoff) + ldsw + _i * 8192), 16, 0, 0); } while (0)
; #define PG8_LDA(dst, b, h) do { _Pragma("unroll") for (int m = 0; m < 4; ++m) _Pragma("unroll") for (int k = 0; k < 2; ++k) dst[m][k] = *(const PG8_LAS bf16x8*)(lds + PG8_SA(b, h) + aoff + m * 2048 + k * 1024); } while (0)
; #define PG8_MMA(ai, bj, At, Bt) do { __builtin_amdgcn_s_setprio(1); _Pragma("unroll") for (int m = 0; m < 4; ++m) _Pragma("unroll") for (int n = 0; n < 2; ++n) _Pragma("unroll") for (int k = 0; k < 2; ++k) \
;         acc[ai][bj][m][n] = __builtin_amdgcn_mfma_f32_16x16x32_bf16(Bt[n][k], At[m][k], acc[ai][bj][m][n], 0, 0, 0); __builtin_amdgcn_s_setprio(0); } while (0)
; #define PG8_WAIT_V(n) asm volatile("s_waitcnt vmcnt(" #n ")" ::: "memory")
; #define PG8_WAIT_L(n) asm volatile("s_waitcnt lgkmcnt(" #n ")" ::: "memory")
; #define PG8_BAR __builtin_amdgcn_s_barrier()
; #define PG8_SCHED __builtin_amdgcn_sched_barrier(0)
; template <class Epi, class Sched, bool ALIGN_EPI = false, bool SP2 = false>
; __device__ __forceinline__ void gemm_phase(PG8_LAS unsigned char* lds, const Gemm g, const Sched& S, const Epi& E) {
;     ...
;             PG8_LDA(At, 1, 1); PG8_STAGE(PG8_SB(1, 0), b3, voffB); PG8_STAGE(PG8_SB(1, 1), b3 + hstep, voffB); PG8_STAGE(PG8_SA(1, 0), a3, voffA);
;             PG8_WAIT_V(8); PG8_WAIT_L(0); PG8_BAR; PG8_MMA(1, 0, At, B0); PG8_MMA(1, 1, At, B1); PG8_BAR; PG8_SCHED;
	s_add_i32 s10, s33, s15
	v_lshl_add_u64 v[158:159], v[158:159], 0, s[40:41]
	s_mov_b32 m0, s10
	ds_read_b128 v[188:191], v164 offset:49152
	ds_read_b128 v[192:195], v164 offset:50176
	ds_read_b128 v[196:199], v164 offset:51200
	ds_read_b128 v[200:203], v164 offset:52224
	ds_read_b128 v[204:207], v164 offset:53248
	ds_read_b128 v[208:211], v164 offset:54272
	ds_read_b128 v[212:215], v164 offset:55296
	ds_read_b128 v[216:219], v164 offset:56320
	global_load_lds_dwordx4 v[158:159], off
	s_add_i32 m0, s10, 0x2000
	s_add_u32 s8, s8, 0x40080
	v_lshl_add_u64 v[158:159], v[182:183], 0, s[40:41]
	s_addc_u32 s9, s9, 0
	s_add_i32 s10, s34, s15
	global_load_lds_dwordx4 v[158:159], off
	v_lshl_add_u64 v[158:159], s[8:9], 0, v[148:149]
	s_mov_b32 m0, s10
	s_nop 0
	global_load_lds_dwordx4 v[158:159], off
	v_lshl_add_u64 v[158:159], s[8:9], 0, v[152:153]
	s_add_i32 m0, s10, 0x2000
	s_nop 0
	global_load_lds_dwordx4 v[158:159], off
	v_lshl_add_u64 v[158:159], v[230:231], 0, s[40:41]
	s_mov_b32 m0, s20
	s_nop 0
	global_load_lds_dwordx4 v[158:159], off
	v_lshl_add_u64 v[158:159], v[232:233], 0, s[40:41]
	s_mov_b32 m0, s21
	s_nop 0
	global_load_lds_dwordx4 v[158:159], off
	s_waitcnt vmcnt(8)
	s_waitcnt lgkmcnt(0)
	s_barrier
	s_setprio 1
	v_mfma_f32_16x16x32_bf16 v[60:63], v[130:133], v[188:191], v[60:63]
	v_mfma_f32_16x16x32_bf16 v[56:59], v[138:141], v[188:191], v[56:59]
	v_mfma_f32_16x16x32_bf16 v[44:47], v[130:133], v[196:199], v[44:47]
	v_mfma_f32_16x16x32_bf16 v[40:43], v[138:141], v[196:199], v[40:43]
	v_mfma_f32_16x16x32_bf16 v[28:31], v[130:133], v[204:207], v[28:31]
	v_mfma_f32_16x16x32_bf16 v[24:27], v[138:141], v[204:207], v[24:27]
	v_mfma_f32_16x16x32_bf16 v[12:15], v[130:133], v[212:215], v[12:15]
	v_mfma_f32_16x16x32_bf16 v[8:11], v[138:141], v[212:215], v[8:11]
	v_mfma_f32_16x16x32_bf16 v[60:63], v[134:137], v[192:195], v[60:63]
	v_mfma_f32_16x16x32_bf16 v[56:59], v[142:145], v[192:195], v[56:59]
	v_mfma_f32_16x16x32_bf16 v[44:47], v[134:137], v[200:203], v[44:47]
	v_mfma_f32_16x16x32_bf16 v[40:43], v[142:145], v[200:203], v[40:43]
	v_mfma_f32_16x16x32_bf16 v[28:31], v[134:137], v[208:211], v[28:31]
	v_mfma_f32_16x16x32_bf16 v[24:27], v[142:145], v[208:211], v[24:27]
	v_mfma_f32_16x16x32_bf16 v[12:15], v[134:137], v[216:219], v[12:15]
	v_mfma_f32_16x16x32_bf16 v[8:11], v[142:145], v[216:219], v[8:11]
	v_mfma_f32_16x16x32_bf16 v[52:55], v[166:169], v[188:191], v[52:55]
	v_mfma_f32_16x16x32_bf16 v[48:51], v[174:177], v[188:191], v[48:51]
	v_mfma_f32_16x16x32_bf16 v[36:39], v[166:169], v[196:199], v[36:39]
	v_mfma_f32_16x16x32_bf16 v[32:35], v[174:177], v[196:199], v[32:35]
	v_mfma_f32_16x16x32_bf16 v[20:23], v[166:169], v[204:207], v[20:23]
	v_mfma_f32_16x16x32_bf16 v[16:19], v[174:177], v[204:207], v[16:19]
	v_mfma_f32_16x16x32_bf16 v[4:7], v[166:169], v[212:215], v[4:7]
	v_mfma_f32_16x16x32_bf16 v[0:3], v[174:177], v[212:215], v[0:3]
	v_mfma_f32_16x16x32_bf16 v[52:55], v[170:173], v[192:195], v[52:55]
	v_mfma_f32_16x16x32_bf16 v[48:51], v[178:181], v[192:195], v[48:51]
	v_mfma_f32_16x16x32_bf16 v[36:39], v[170:173], v[200:203], v[36:39]
	v_mfma_f32_16x16x32_bf16 v[32:35], v[178:181], v[200:203], v[32:35]
	v_mfma_f32_16x16x32_bf16 v[20:23], v[170:173], v[208:211], v[20:23]
	v_mfma_f32_16x16x32_bf16 v[16:19], v[178:181], v[208:211], v[16:19]
	v_mfma_f32_16x16x32_bf16 v[4:7], v[170:173], v[216:219], v[4:7]
	v_mfma_f32_16x16x32_bf16 v[0:3], v[178:181], v[216:219], v[0:3]
	s_setprio 0
	s_barrier
	s_add_i32 s29, s29, 2
	s_add_u32 s6, s6, 0x100
	s_addc_u32 s7, s7, 0
	s_add_u32 s27, s27, 0x100
	s_addc_u32 s28, s28, 0
	s_cmp_gt_u32 s29, 13
	s_cbranch_scc0 .LBB0_473
	s_and_b64 vcc, exec, s[62:63]
	s_cbranch_vccz .LBB0_476
	s_barrier
